# stacked safe edits: attention counted lgkmcnt waits; GEMM setprio moved off the barrier-to-MFMA path; nt on the f32 output-row stores
# baseline (speedup 1.0000x reference)
; __device__ __forceinline__ void ln_rows_b(const Frame& F, const bf16* src, float* dstf, bf16* dstb, float* must, const float* gam, const float* bet, int nrows, bool poison) {
;     ...
;         float v[4][8]; float s = 0.f;
; #pragma unroll
;         for (int j = 0; j < 4; ++j) { const v4u w = wc[j];
;             v[j][0] = __uint_as_float(w.x << 16); v[j][1] = __uint_as_float(w.x & 0xffff0000u); v[j][2] = __uint_as_float(w.y << 16); v[j][3] = __uint_as_float(w.y & 0xffff0000u);
;             v[j][4] = __uint_as_float(w.z << 16); v[j][5] = __uint_as_float(w.z & 0xffff0000u); v[j][6] = __uint_as_float(w.w << 16); v[j][7] = __uint_as_float(w.w & 0xffff0000u);
; #pragma unroll
;             for (int e = 0; e < 8; ++e) s += v[j][e]; }
;         const float mean = wave_sum(s, F.lane) * (1.f / DM); float s2 = 0.f;
; #pragma unroll
;         for (int j = 0; j < 4; ++j)
; #pragma unroll
;             for (int e = 0; e < 8; ++e) { v[j][e] -= mean; s2 += v[j][e] * v[j][e]; }
;         const float rstd = 1.f / sqrtf(wave_sum(s2, F.lane) * (1.f / DM) + LN_EPS);
.LBB0_216:
	v_lshlrev_b32_e32 v54, 16, v30
	v_and_b32_e32 v55, 0xffff0000, v30
	v_lshlrev_b32_e32 v80, 16, v18
	v_and_b32_e32 v81, 0xffff0000, v18
	v_add_f32_e32 v18, 0, v54
	v_lshlrev_b32_e32 v30, 16, v31
	v_add_f32_e32 v18, v18, v55
	v_and_b32_e32 v31, 0xffff0000, v31
	v_add_f32_e32 v18, v18, v30
	v_lshlrev_b32_e32 v56, 16, v32
	v_add_f32_e32 v18, v18, v31
	v_and_b32_e32 v57, 0xffff0000, v32
	v_add_f32_e32 v18, v18, v56
	v_lshlrev_b32_e32 v32, 16, v33
	v_add_f32_e32 v18, v18, v57
	v_and_b32_e32 v33, 0xffff0000, v33
	v_add_f32_e32 v18, v18, v32
	v_lshlrev_b32_e32 v58, 16, v26
	v_add_f32_e32 v18, v18, v33
	v_and_b32_e32 v59, 0xffff0000, v26
	v_add_f32_e32 v18, v18, v58
	v_lshlrev_b32_e32 v26, 16, v27
	v_add_f32_e32 v18, v18, v59
	v_and_b32_e32 v27, 0xffff0000, v27
	v_add_f32_e32 v18, v18, v26
	v_lshlrev_b32_e32 v60, 16, v28
	v_add_f32_e32 v18, v18, v27
	v_and_b32_e32 v61, 0xffff0000, v28
	v_add_f32_e32 v18, v18, v60
	v_lshlrev_b32_e32 v28, 16, v29
	v_add_f32_e32 v18, v18, v61
	v_and_b32_e32 v29, 0xffff0000, v29
	v_add_f32_e32 v18, v18, v28
	s_waitcnt lgkmcnt(0)
	v_lshlrev_b32_e32 v76, 16, v22
	v_add_f32_e32 v18, v18, v29
	v_and_b32_e32 v77, 0xffff0000, v22
	v_add_f32_e32 v18, v18, v76
	v_lshlrev_b32_e32 v22, 16, v23
	v_add_f32_e32 v18, v18, v77
	v_and_b32_e32 v23, 0xffff0000, v23
	v_add_f32_e32 v18, v18, v22
	v_lshlrev_b32_e32 v78, 16, v24
	v_add_f32_e32 v18, v18, v23
	v_and_b32_e32 v79, 0xffff0000, v24
	v_add_f32_e32 v18, v18, v78
	v_lshlrev_b32_e32 v24, 16, v25
	v_add_f32_e32 v18, v18, v79
	v_and_b32_e32 v25, 0xffff0000, v25
	v_add_f32_e32 v18, v18, v24
	v_add_f32_e32 v18, v18, v25
	v_add_f32_e32 v18, v18, v80
	v_lshlrev_b32_e32 v82, 16, v19
	v_add_f32_e32 v18, v18, v81
	v_and_b32_e32 v83, 0xffff0000, v19
	v_add_f32_e32 v18, v18, v82
	v_lshlrev_b32_e32 v84, 16, v20
	v_add_f32_e32 v18, v18, v83
	v_and_b32_e32 v85, 0xffff0000, v20
	v_add_f32_e32 v18, v18, v84
	v_lshlrev_b32_e32 v86, 16, v21
	v_add_f32_e32 v18, v18, v85
	v_and_b32_e32 v87, 0xffff0000, v21
	v_add_f32_e32 v18, v18, v86
	v_add_f32_e32 v18, v18, v87
	ds_bpermute_b32 v19, v1, v18
	s_andn2_b64 vcc, exec, s[12:13]
	s_waitcnt lgkmcnt(0)
	v_add_f32_e32 v18, v18, v19
	ds_bpermute_b32 v19, v70, v18
	s_waitcnt lgkmcnt(0)
	v_add_f32_e32 v18, v18, v19
	ds_bpermute_b32 v19, v71, v18
	s_waitcnt lgkmcnt(0)
	v_add_f32_e32 v18, v18, v19
	ds_bpermute_b32 v19, v72, v18
	s_waitcnt lgkmcnt(0)
	v_add_f32_e32 v18, v18, v19
	ds_bpermute_b32 v19, v73, v18
	s_waitcnt lgkmcnt(0)
	v_add_f32_e32 v18, v18, v19
	ds_bpermute_b32 v19, v74, v18
	s_waitcnt lgkmcnt(0)
	v_add_f32_e32 v18, v18, v19
	v_mul_f32_e32 v88, 0x3a000000, v18
	v_pk_add_f32 v[62:63], v[54:55], v[88:89] op_sel_hi:[1,0] neg_lo:[0,1] neg_hi:[0,1]
	v_pk_add_f32 v[64:65], v[30:31], v[88:89] op_sel_hi:[1,0] neg_lo:[0,1] neg_hi:[0,1]
	v_pk_mul_f32 v[90:91], v[62:63], v[62:63]
	v_pk_mul_f32 v[92:93], v[64:65], v[64:65]
	v_add_f32_e32 v75, v90, v91
	v_pk_add_f32 v[66:67], v[56:57], v[88:89] op_sel_hi:[1,0] neg_lo:[0,1] neg_hi:[0,1]
	v_add_f32_e32 v75, v92, v75
	v_pk_mul_f32 v[94:95], v[66:67], v[66:67]
	v_add_f32_e32 v75, v93, v75
	v_pk_add_f32 v[68:69], v[32:33], v[88:89] op_sel_hi:[1,0] neg_lo:[0,1] neg_hi:[0,1]
	v_add_f32_e32 v75, v94, v75
	v_pk_mul_f32 v[96:97], v[68:69], v[68:69]
	v_add_f32_e32 v75, v95, v75
	v_pk_add_f32 v[54:55], v[58:59], v[88:89] op_sel_hi:[1,0] neg_lo:[0,1] neg_hi:[0,1]
	v_add_f32_e32 v75, v96, v75
	v_pk_mul_f32 v[98:99], v[54:55], v[54:55]
	v_add_f32_e32 v75, v97, v75
	v_pk_add_f32 v[56:57], v[26:27], v[88:89] op_sel_hi:[1,0] neg_lo:[0,1] neg_hi:[0,1]
	v_add_f32_e32 v75, v98, v75
	v_pk_mul_f32 v[100:101], v[56:57], v[56:57]
	v_add_f32_e32 v75, v99, v75
	v_pk_add_f32 v[58:59], v[60:61], v[88:89] op_sel_hi:[1,0] neg_lo:[0,1] neg_hi:[0,1]
	v_add_f32_e32 v75, v100, v75
	v_pk_mul_f32 v[102:103], v[58:59], v[58:59]
	v_add_f32_e32 v75, v101, v75
	v_pk_add_f32 v[60:61], v[28:29], v[88:89] op_sel_hi:[1,0] neg_lo:[0,1] neg_hi:[0,1]
	v_add_f32_e32 v75, v102, v75
	v_pk_mul_f32 v[104:105], v[60:61], v[60:61]
	v_add_f32_e32 v75, v103, v75
	v_pk_add_f32 v[26:27], v[76:77], v[88:89] op_sel_hi:[1,0] neg_lo:[0,1] neg_hi:[0,1]
	v_add_f32_e32 v75, v104, v75
	v_pk_mul_f32 v[76:77], v[26:27], v[26:27]
	v_add_f32_e32 v75, v105, v75
	v_pk_add_f32 v[28:29], v[22:23], v[88:89] op_sel_hi:[1,0] neg_lo:[0,1] neg_hi:[0,1]
	v_add_f32_e32 v75, v76, v75
	v_pk_mul_f32 v[106:107], v[28:29], v[28:29]
	v_add_f32_e32 v75, v77, v75
	v_pk_add_f32 v[30:31], v[78:79], v[88:89] op_sel_hi:[1,0] neg_lo:[0,1] neg_hi:[0,1]
	v_add_f32_e32 v75, v106, v75
	v_pk_mul_f32 v[78:79], v[30:31], v[30:31]
	v_add_f32_e32 v75, v107, v75
	v_pk_add_f32 v[32:33], v[24:25], v[88:89] op_sel_hi:[1,0] neg_lo:[0,1] neg_hi:[0,1]
	v_add_f32_e32 v75, v78, v75
	v_pk_mul_f32 v[108:109], v[32:33], v[32:33]
	v_add_f32_e32 v75, v79, v75
	v_pk_add_f32 v[18:19], v[80:81], v[88:89] op_sel_hi:[1,0] neg_lo:[0,1] neg_hi:[0,1]
	v_add_f32_e32 v75, v108, v75
	v_pk_mul_f32 v[80:81], v[18:19], v[18:19]
	v_add_f32_e32 v75, v109, v75
	v_pk_add_f32 v[20:21], v[82:83], v[88:89] op_sel_hi:[1,0] neg_lo:[0,1] neg_hi:[0,1]
	v_add_f32_e32 v75, v80, v75
	v_pk_mul_f32 v[82:83], v[20:21], v[20:21]
	v_add_f32_e32 v75, v81, v75
	v_pk_add_f32 v[22:23], v[84:85], v[88:89] op_sel_hi:[1,0] neg_lo:[0,1] neg_hi:[0,1]
	v_add_f32_e32 v75, v82, v75
	v_pk_mul_f32 v[84:85], v[22:23], v[22:23]
	v_add_f32_e32 v75, v83, v75
	v_pk_add_f32 v[24:25], v[86:87], v[88:89] op_sel_hi:[1,0] neg_lo:[0,1] neg_hi:[0,1]
	v_add_f32_e32 v75, v84, v75
	v_pk_mul_f32 v[86:87], v[24:25], v[24:25]
	v_add_f32_e32 v75, v85, v75
	v_add_f32_e32 v75, v86, v75
	v_add_f32_e32 v75, v87, v75
	ds_bpermute_b32 v76, v1, v75
	s_waitcnt lgkmcnt(0)
	v_add_f32_e32 v75, v75, v76
	ds_bpermute_b32 v76, v70, v75
	s_waitcnt lgkmcnt(0)
	v_add_f32_e32 v75, v75, v76
	ds_bpermute_b32 v76, v71, v75
	s_waitcnt lgkmcnt(0)
	v_add_f32_e32 v75, v75, v76
	ds_bpermute_b32 v76, v72, v75
	s_waitcnt lgkmcnt(0)
	v_add_f32_e32 v75, v75, v76
	ds_bpermute_b32 v76, v73, v75
	s_waitcnt lgkmcnt(0)
	v_add_f32_e32 v75, v75, v76
	ds_bpermute_b32 v76, v74, v75
	s_cbranch_vccnz .LBB0_213
; #define GAS __attribute__((address_space(1)))
; __device__ __forceinline__ unsigned pk2(float lo, float hi) { return f2bf(lo) | (f2bf(hi) << 16); }
; __device__ __forceinline__ void ln_rows_b(const Frame& F, const bf16* src, float* dstf, bf16* dstb, float* must, const float* gam, const float* bet, int nrows, bool poison) {
;     ...
;         const float rstd = 1.f / sqrtf(wave_sum(s2, F.lane) * (1.f / DM) + LN_EPS);
;         if (must && F.lane == 0) { float2 o2; o2.x = mean; o2.y = rstd; *(float2*)(must + (size_t)m * 2) = o2; }
; #pragma unroll
;         for (int j = 0; j < 4; ++j) { const int c0 = (64 * j + F.lane) * 8;
;             const f32x4 g0 = *(const GAS f32x4*)(gam + c0), g1 = *(const GAS f32x4*)(gam + c0 + 4), b0 = *(const GAS f32x4*)(bet + c0), b1 = *(const GAS f32x4*)(bet + c0 + 4);
;             f32x4 o0 = (f32x4){v[j][0], v[j][1], v[j][2], v[j][3]} * rstd * g0 + b0, o1 = (f32x4){v[j][4], v[j][5], v[j][6], v[j][7]} * rstd * g1 + b1;
;             if (poison) { const float q = __builtin_nanf(""); o0 = (f32x4){q, q, q, q}; o1 = o0; }
;             if (dstf) { *(GAS f32x4*)(dstf + (size_t)m * DM + c0) = o0; *(GAS f32x4*)(dstf + (size_t)m * DM + c0 + 4) = o1; }
;             if (dstb) { v4u w; w.x = pk2(o0.x, o0.y); w.y = pk2(o0.z, o0.w); w.z = pk2(o1.x, o1.y); w.w = pk2(o1.z, o1.w); *(GAS v4u*)(dstb + (size_t)m * DM + c0) = w; } }
	global_load_dwordx4 v[78:81], v[36:37], off offset:16
	global_load_dwordx4 v[82:85], v[34:35], off offset:16
	global_load_dwordx4 v[86:89], v[34:35], off
	global_load_dwordx4 v[90:93], v[36:37], off
	s_waitcnt lgkmcnt(0)
	v_add_f32_e32 v75, v75, v76
	v_fmamk_f32 v75, v75, 0x3a000000, v244
	v_mul_f32_e32 v76, 0x4f800000, v75
	v_cmp_gt_f32_e32 vcc, s47, v75
	s_nop 1
	v_cndmask_b32_e32 v75, v75, v76, vcc
	v_sqrt_f32_e32 v76, v75
	s_nop 0
	v_add_u32_e32 v77, -1, v76
	v_add_u32_e32 v94, 1, v76
	v_fma_f32 v95, -v77, v76, v75
	v_fma_f32 v96, -v94, v76, v75
	v_cmp_ge_f32_e64 s[6:7], 0, v95
	s_nop 1
	v_cndmask_b32_e64 v76, v76, v77, s[6:7]
	v_cmp_lt_f32_e64 s[6:7], 0, v96
	s_nop 1
	v_cndmask_b32_e64 v76, v76, v94, s[6:7]
	v_mul_f32_e32 v77, 0x37800000, v76
	v_cndmask_b32_e32 v76, v76, v77, vcc
	v_cmp_class_f32_e32 vcc, v75, v246
	s_nop 1
	v_cndmask_b32_e32 v75, v76, v75, vcc
	v_div_scale_f32 v76, s[6:7], v75, v75, 1.0
	v_rcp_f32_e32 v77, v76
	v_div_scale_f32 v94, vcc, 1.0, v75, 1.0
	v_fma_f32 v95, -v76, v77, 1.0
	v_fmac_f32_e32 v77, v95, v77
	v_mul_f32_e32 v95, v94, v77
	v_fma_f32 v96, -v76, v95, v94
	v_fmac_f32_e32 v95, v96, v77
	v_fma_f32 v76, -v76, v95, v94
	v_div_fmas_f32 v76, v76, v77, v95
	v_div_fixup_f32 v94, v76, v75, 1.0
	v_pk_mul_f32 v[66:67], v[66:67], v[94:95] op_sel_hi:[1,0]
	v_pk_mul_f32 v[68:69], v[68:69], v[94:95] op_sel_hi:[1,0]
	v_pk_mul_f32 v[76:77], v[62:63], v[94:95] op_sel_hi:[1,0]
	v_pk_mul_f32 v[96:97], v[64:65], v[94:95] op_sel_hi:[1,0]
	v_pk_mul_f32 v[60:61], v[60:61], v[94:95] op_sel_hi:[1,0]
	v_pk_mul_f32 v[58:59], v[58:59], v[94:95] op_sel_hi:[1,0]
	v_pk_mul_f32 v[32:33], v[32:33], v[94:95] op_sel_hi:[1,0]
	v_pk_mul_f32 v[30:31], v[30:31], v[94:95] op_sel_hi:[1,0]
	v_pk_mul_f32 v[24:25], v[24:25], v[94:95] op_sel_hi:[1,0]
	v_pk_mul_f32 v[22:23], v[22:23], v[94:95] op_sel_hi:[1,0]
	s_waitcnt vmcnt(2)
	v_pk_fma_f32 v[64:65], v[68:69], v[80:81], v[84:85]
	v_pk_fma_f32 v[62:63], v[66:67], v[78:79], v[82:83]
	s_waitcnt vmcnt(0)
	v_pk_fma_f32 v[68:69], v[96:97], v[92:93], v[88:89]
	v_pk_fma_f32 v[66:67], v[76:77], v[90:91], v[86:87]
	global_store_dwordx4 v[50:51], v[66:69], off offset:-4096 nt
	global_store_dwordx4 v[50:51], v[62:65], off offset:-4080 nt
	global_load_dwordx4 v[62:65], v[40:41], off offset:16
	s_nop 0
	global_load_dwordx4 v[66:69], v[38:39], off offset:16
	global_load_dwordx4 v[76:79], v[38:39], off
	global_load_dwordx4 v[80:83], v[40:41], off
	v_pk_mul_f32 v[84:85], v[56:57], v[94:95] op_sel_hi:[1,0]
	v_pk_mul_f32 v[86:87], v[54:55], v[94:95] op_sel_hi:[1,0]
	s_waitcnt vmcnt(2)
	v_pk_fma_f32 v[54:55], v[58:59], v[62:63], v[66:67]
	v_pk_fma_f32 v[56:57], v[60:61], v[64:65], v[68:69]
	s_waitcnt vmcnt(0)
	v_pk_fma_f32 v[58:59], v[86:87], v[80:81], v[76:77]
	v_pk_fma_f32 v[60:61], v[84:85], v[82:83], v[78:79]
	global_store_dwordx4 v[50:51], v[58:61], off offset:-2048 nt
	global_store_dwordx4 v[50:51], v[54:57], off offset:-2032 nt
	global_load_dwordx4 v[54:57], v[44:45], off offset:16
	s_nop 0
	global_load_dwordx4 v[58:61], v[42:43], off offset:16
	global_load_dwordx4 v[62:65], v[42:43], off
	global_load_dwordx4 v[66:69], v[44:45], off
	v_pk_mul_f32 v[76:77], v[28:29], v[94:95] op_sel_hi:[1,0]
	v_pk_mul_f32 v[78:79], v[26:27], v[94:95] op_sel_hi:[1,0]
	s_waitcnt vmcnt(2)
	v_pk_fma_f32 v[26:27], v[30:31], v[54:55], v[58:59]
	v_pk_fma_f32 v[28:29], v[32:33], v[56:57], v[60:61]
	s_waitcnt vmcnt(0)
	v_pk_fma_f32 v[30:31], v[78:79], v[66:67], v[62:63]
	v_pk_fma_f32 v[32:33], v[76:77], v[68:69], v[64:65]
	global_store_dwordx4 v[50:51], v[30:33], off nt
	global_store_dwordx4 v[50:51], v[26:29], off offset:16 nt
	global_load_dwordx4 v[26:29], v[48:49], off offset:16
	s_nop 0
	global_load_dwordx4 v[30:33], v[46:47], off offset:16
	global_load_dwordx4 v[54:57], v[46:47], off
	global_load_dwordx4 v[58:61], v[48:49], off
	v_pk_mul_f32 v[62:63], v[20:21], v[94:95] op_sel_hi:[1,0]
	v_pk_mul_f32 v[64:65], v[18:19], v[94:95] op_sel_hi:[1,0]
	s_waitcnt vmcnt(2)
	v_pk_fma_f32 v[18:19], v[22:23], v[26:27], v[30:31]
	v_pk_fma_f32 v[20:21], v[24:25], v[28:29], v[32:33]
	s_waitcnt vmcnt(0)
	v_pk_fma_f32 v[22:23], v[64:65], v[58:59], v[54:55]
	v_pk_fma_f32 v[24:25], v[62:63], v[60:61], v[56:57]
	global_store_dwordx4 v[50:51], v[22:25], off offset:2048 nt
	global_store_dwordx4 v[50:51], v[18:21], off offset:2064 nt
	s_branch .LBB0_213

; #define SBAR() __builtin_amdgcn_sched_barrier(0)
; #define KF(a, o) (*(const __attribute__((address_space(3))) bf16x8*)((a) + (o)))
; template <class Hook> __device__ __forceinline__ void qk_sub(f32x16& p, ldsc_t k0, ldsc_t k1, ldsc_t k2, ldsc_t k3, int kd, const bf16x8* qr, const Hook& hook) {
;     ...
;   SBAR();
;   bf16x8 f0 = KF(k0, 0), f1 = KF(k1, 0), f2 = KF(k2, 0), f3 = KF(k3, 0); SBAR(); __builtin_amdgcn_s_setprio(1);
;   p = __builtin_amdgcn_mfma_f32_32x32x16_bf16(f0, qr[0], f32x16{}, 0, 0, 0); f0 = KF(k0 + kd, 0); SBAR();
;   p = __builtin_amdgcn_mfma_f32_32x32x16_bf16(f1, qr[1], p, 0, 0, 0); f1 = KF(k1 + kd, 0); hook(0); SBAR();
;   p = __builtin_amdgcn_mfma_f32_32x32x16_bf16(f2, qr[2], p, 0, 0, 0); f2 = KF(k2 + kd, 0); SBAR();
;   p = __builtin_amdgcn_mfma_f32_32x32x16_bf16(f3, qr[3], p, 0, 0, 0); f3 = KF(k3 + kd, 0); hook(1); SBAR();
;   p = __builtin_amdgcn_mfma_f32_32x32x16_bf16(f0, qr[4], p, 0, 0, 0); SBAR();
;   p = __builtin_amdgcn_mfma_f32_32x32x16_bf16(f1, qr[5], p, 0, 0, 0); hook(2); SBAR();
;   p = __builtin_amdgcn_mfma_f32_32x32x16_bf16(f2, qr[6], p, 0, 0, 0); SBAR();
;   p = __builtin_amdgcn_mfma_f32_32x32x16_bf16(f3, qr[7], p, 0, 0, 0); hook(3); __builtin_amdgcn_s_setprio(0); SBAR();
; __device__ __forceinline__ void softmax_sub(f32x16& p, float& m_reg, float& l_reg, bf16x8& pa0, bf16x8& pa1, f32x16 (&o)[8], float* al_l, int r32, int hi, int dj, const float* tab, float cL, float cR) {
;     ...
;   if (dj <= -159) cb = cL;
;   else if (dj >= 159) cb = cR;
;   else { cb = 0.f; const int ib = dj - r32 + 4 * hi + 128;
; #pragma unroll
;     for (int r = 0; r < 16; ++r) { const int i0 = ib + (r & 3) + 8 * (r >> 2); p[r] += tab[min(max(i0, 0), 256)]; } }
.LBB0_548:
	s_waitcnt vmcnt(0)
	s_add_i32 s4, s27, 0xffff0000
	s_barrier
	s_and_b32 s29, s4, 0x10000
	v_add_u32_e32 v1, s29, v252
	v_add_u32_e32 v198, s29, v253
	v_add_u32_e32 v199, s29, v241
	v_add_u32_e32 v202, s29, v244
	ds_read_b128 v[130:133], v1
	ds_read_b128 v[134:137], v198
	ds_read_b128 v[138:141], v199
	ds_read_b128 v[142:145], v202
	s_setprio 1
	s_waitcnt lgkmcnt(3)
	v_mfma_f32_32x32x16_bf16 v[146:161], v[130:133], v[190:193], 0
	v_add_u32_e32 v206, v1, v251
	ds_read_b128 v[130:133], v206
	s_and_b32 s24, s27, 0x10000
	s_add_i32 s28, s23, s24
	v_lshl_add_u64 v[194:195], s[8:9], 0, v[226:227]
	v_add_u32_e32 v210, v198, v251
	v_lshl_add_u64 v[196:197], v[194:195], 0, s[92:93]
	s_mov_b32 m0, s28
	s_waitcnt lgkmcnt(3)
	v_mfma_f32_32x32x16_bf16 v[146:161], v[134:137], v[186:189], v[146:161]
	ds_read_b128 v[134:137], v210
	global_load_lds_dwordx4 v[196:197], off
	s_waitcnt lgkmcnt(3)
	v_mfma_f32_32x32x16_bf16 v[146:161], v[138:141], v[182:185], v[146:161]
	v_add_u32_e32 v212, v199, v251
	ds_read_b128 v[138:141], v212
	v_add_u32_e32 v213, v202, v251
	s_add_i32 m0, s28, 0x2000
	v_lshl_add_u64 v[196:197], v[194:195], 0, s[94:95]
	s_waitcnt lgkmcnt(3)
	v_mfma_f32_32x32x16_bf16 v[146:161], v[142:145], v[178:181], v[146:161]
	ds_read_b128 v[142:145], v213
	global_load_lds_dwordx4 v[196:197], off
	s_waitcnt lgkmcnt(3)
	v_mfma_f32_32x32x16_bf16 v[146:161], v[130:133], v[174:177], v[146:161]
	s_mov_b64 s[4:5], 0xc0100
	s_add_i32 m0, s28, 0x4000
	v_lshl_add_u64 v[130:131], v[194:195], 0, s[4:5]
	global_load_lds_dwordx4 v[130:131], off
	s_waitcnt lgkmcnt(2)
	v_mfma_f32_32x32x16_bf16 v[146:161], v[134:137], v[170:173], v[146:161]
	s_waitcnt lgkmcnt(1)
	v_mfma_f32_32x32x16_bf16 v[146:161], v[138:141], v[166:169], v[146:161]
	s_mov_b64 s[4:5], 0x120100
	s_add_i32 m0, s28, 0x6000
	v_lshl_add_u64 v[130:131], v[194:195], 0, s[4:5]
	global_load_lds_dwordx4 v[130:131], off
	s_waitcnt lgkmcnt(0)
	v_mfma_f32_32x32x16_bf16 v[146:161], v[142:145], v[162:165], v[146:161]
	s_setprio 0
	ds_read_b128 v[130:133], v1 offset:8192
	ds_read_b128 v[194:197], v198 offset:8192
	ds_read_b128 v[198:201], v199 offset:8192
	ds_read_b128 v[202:205], v202 offset:8192
	s_setprio 1
	s_waitcnt lgkmcnt(3)
	v_mfma_f32_32x32x16_bf16 v[130:145], v[130:133], v[190:193], 0
	ds_read_b128 v[206:209], v206 offset:8192
	s_waitcnt lgkmcnt(3)
	v_mfma_f32_32x32x16_bf16 v[130:145], v[194:197], v[186:189], v[130:145]
	ds_read_b128 v[194:197], v210 offset:8192
	s_waitcnt lgkmcnt(3)
	v_mfma_f32_32x32x16_bf16 v[130:145], v[198:201], v[182:185], v[130:145]
	ds_read_b128 v[198:201], v212 offset:8192
	s_waitcnt lgkmcnt(3)
	v_mfma_f32_32x32x16_bf16 v[130:145], v[202:205], v[178:181], v[130:145]
	ds_read_b128 v[202:205], v213 offset:8192
	s_waitcnt lgkmcnt(3)
	v_mfma_f32_32x32x16_bf16 v[130:145], v[206:209], v[174:177], v[130:145]
	s_waitcnt lgkmcnt(2)
	v_mfma_f32_32x32x16_bf16 v[130:145], v[194:197], v[170:173], v[130:145]
	s_waitcnt lgkmcnt(1)
	v_mfma_f32_32x32x16_bf16 v[130:145], v[198:201], v[166:169], v[130:145]
	s_waitcnt lgkmcnt(0)
	v_mfma_f32_32x32x16_bf16 v[130:145], v[202:205], v[162:165], v[130:145]
	s_setprio 0
	v_add_u32_e32 v1, s29, v250
	ds_read_b64_tr_b16 v[206:207], v1 offset:32768
	ds_read_b64_tr_b16 v[208:209], v1 offset:36864
	ds_read_b64_tr_b16 v[200:201], v1 offset:37376
	ds_read_b64_tr_b16 v[198:199], v1 offset:33280
	ds_read_b64_tr_b16 v[202:203], v1 offset:40960
	ds_read_b64_tr_b16 v[204:205], v1 offset:45056
	ds_read_b64_tr_b16 v[196:197], v1 offset:45568
	ds_read_b64_tr_b16 v[194:195], v1 offset:41472
	s_cmpk_lt_i32 s26, 0xff62
	s_cbranch_scc1 .LBB0_551
	s_cmpk_gt_i32 s26, 0x9e
	s_cbranch_scc1 .LBB0_552
	v_add_u32_e32 v210, s26, v245
	v_add_u32_e32 v210, 0x80, v210
	v_mov_b32_e32 v212, 0x100
	v_med3_i32 v212, v210, 0, v212
	v_lshl_add_u32 v220, v212, 2, s20
	v_max_i32_e32 v212, -1, v210
	v_add_u32_e32 v212, 1, v212
	v_min_u32_e32 v212, 0x100, v212
	v_lshl_add_u32 v221, v212, 2, s20
	v_max_i32_e32 v212, -2, v210
	v_add_u32_e32 v212, 2, v212
	v_min_u32_e32 v212, 0x100, v212
	v_lshl_add_u32 v222, v212, 2, s20
	v_max_i32_e32 v212, -3, v210
	v_add_u32_e32 v212, 3, v212
	v_min_u32_e32 v212, 0x100, v212
	v_lshl_add_u32 v223, v212, 2, s20
	v_max_i32_e32 v212, -8, v210
	v_add_u32_e32 v212, 8, v212
	v_min_u32_e32 v212, 0x100, v212
	v_lshl_add_u32 v224, v212, 2, s20
	v_max_i32_e32 v212, -9, v210
	v_add_u32_e32 v212, 9, v212
	v_min_u32_e32 v212, 0x100, v212
	v_lshl_add_u32 v225, v212, 2, s20
	v_max_i32_e32 v212, -10, v210
	v_add_u32_e32 v212, 10, v212
	v_min_u32_e32 v212, 0x100, v212
	v_lshl_add_u32 v232, v212, 2, s20
	v_max_i32_e32 v212, -11, v210
	v_add_u32_e32 v212, 11, v212
	v_min_u32_e32 v212, 0x100, v212
	v_lshl_add_u32 v233, v212, 2, s20
	v_max_i32_e32 v212, -16, v210
	v_max_i32_e32 v213, 0xffffffef, v210
	v_max_i32_e32 v214, 0xffffffee, v210
	v_max_i32_e32 v215, 0xffffffed, v210
	v_max_i32_e32 v216, 0xffffffe8, v210
	v_max_i32_e32 v217, 0xffffffe7, v210
	v_max_i32_e32 v218, 0xffffffe6, v210
	v_add_u32_e32 v212, 16, v212
	v_add_u32_e32 v213, 17, v213
	v_add_u32_e32 v214, 18, v214
	v_add_u32_e32 v215, 19, v215
	v_add_u32_e32 v216, 24, v216
	v_add_u32_e32 v217, 25, v217
	v_add_u32_e32 v218, 26, v218
	v_max_i32_e32 v210, 0xffffffe5, v210
	v_min_u32_e32 v212, 0x100, v212
	v_min_u32_e32 v213, 0x100, v213
	v_min_u32_e32 v214, 0x100, v214
	v_min_u32_e32 v215, 0x100, v215
	v_min_u32_e32 v216, 0x100, v216
	v_min_u32_e32 v217, 0x100, v217
	v_min_u32_e32 v218, 0x100, v218
	v_add_u32_e32 v210, 27, v210
	v_lshl_add_u32 v212, v212, 2, s20
	v_lshl_add_u32 v213, v213, 2, s20
	v_lshl_add_u32 v214, v214, 2, s20
	v_lshl_add_u32 v215, v215, 2, s20
	v_lshl_add_u32 v216, v216, 2, s20
	v_lshl_add_u32 v217, v217, 2, s20
	v_lshl_add_u32 v218, v218, 2, s20
	v_min_u32_e32 v210, 0x100, v210
	v_lshl_add_u32 v210, v210, 2, s20
	ds_read_b32 v212, v212
	ds_read_b32 v213, v213
	ds_read_b32 v214, v214
	ds_read_b32 v215, v215
	ds_read_b32 v216, v216
	ds_read_b32 v217, v217
	ds_read_b32 v218, v218
	ds_read_b32 v219, v210
	ds_read_b32 v220, v220
	ds_read_b32 v221, v221
	ds_read_b32 v222, v222
	ds_read_b32 v223, v223
	ds_read_b32 v224, v224
	ds_read_b32 v225, v225
	ds_read_b32 v232, v232
	ds_read_b32 v233, v233
	s_waitcnt lgkmcnt(0)
	v_pk_add_f32 v[160:161], v[160:161], v[218:219]
	v_pk_add_f32 v[158:159], v[158:159], v[216:217]
	v_pk_add_f32 v[156:157], v[156:157], v[214:215]
	v_pk_add_f32 v[154:155], v[154:155], v[212:213]
	v_pk_add_f32 v[152:153], v[152:153], v[232:233]
	v_pk_add_f32 v[150:151], v[150:151], v[224:225]
	v_pk_add_f32 v[148:149], v[148:149], v[222:223]
	v_pk_add_f32 v[146:147], v[146:147], v[220:221]
	s_mov_b32 s29, 0
	s_branch .LBB0_553

; #define SBAR() __builtin_amdgcn_sched_barrier(0)
; template <int D0, int S> __device__ __forceinline__ VG vload(ldsc_t vb) { VG g; g.l0 = vtr(vb + v_rd_off(D0, 2 * S, 0)); g.h0 = vtr(vb + v_rd_off(D0, 2 * S, 1)); g.l1 = vtr(vb + v_rd_off(D0, 2 * S + 1, 0)); g.h1 = vtr(vb + v_rd_off(D0, 2 * S + 1, 1)); return g; }
; __device__ __forceinline__ void softmax_sub(f32x16& p, float& m_reg, float& l_reg, bf16x8& pa0, bf16x8& pa1, f32x16 (&o)[8], float* al_l, int r32, int hi, int dj, const float* tab, float cL, float cR) {
;     ...
;   const float mnC = (cb - mn) * C;
;   float ps = 0;
; #pragma unroll
;   for (int r = 0; r < 16; ++r) { p[r] = __builtin_amdgcn_exp2f(fmaf(p[r], C, mnC)); ps += p[r]; }
;   { auto rr = __builtin_amdgcn_permlane32_swap(__float_as_uint(ps), __float_as_uint(ps), false, false);
;     ps = __uint_as_float(rr[0]) + __uint_as_float(rr[1]); }
;   l_reg = l_reg * alpha + ps;
;     ...
;   PK4(p, 0, pa0); PK4(p, 8, pa1);
;     ...
; }
; template <int S, class Dma> __device__ __forceinline__ void pv_run(f32x16 (&o)[8], ldsc_t vb, VG g0, VG g1, bf16x8 pa0, bf16x8 pa1, const Dma& dma) {
;   SBAR(); __builtin_amdgcn_s_setprio(1);
;   vmma(o[0], g0, pa0, pa1); dma(0); SBAR(); g0 = vload<2, S>(vb); SBAR();
;   vmma(o[1], g1, pa0, pa1); dma(1); SBAR(); g1 = vload<3, S>(vb); SBAR();
;   vmma(o[2], g0, pa0, pa1); dma(2); SBAR(); g0 = vload<4, S>(vb); SBAR();
;   vmma(o[3], g1, pa0, pa1); dma(3); SBAR(); g1 = vload<5, S>(vb); SBAR();
;   vmma(o[4], g0, pa0, pa1); dma(4); SBAR(); g0 = vload<6, S>(vb); SBAR();
;   vmma(o[5], g1, pa0, pa1); dma(5); SBAR(); g1 = vload<7, S>(vb); SBAR();
;   vmma(o[6], g0, pa0, pa1); dma(6); SBAR(); vmma(o[7], g1, pa0, pa1); dma(7); __builtin_amdgcn_s_setprio(0); SBAR();
.LBB0_555:
	v_sub_f32_e32 v211, s29, v210
	v_mul_f32_e32 v211, 0x3e0293ee, v211
	v_fmamk_f32 v146, v146, 0x3e0293ee, v211
	v_exp_f32_e32 v146, v146
	v_fmamk_f32 v147, v147, 0x3e0293ee, v211
	v_exp_f32_e32 v147, v147
	v_fmamk_f32 v148, v148, 0x3e0293ee, v211
	v_exp_f32_e32 v148, v148
	v_fmamk_f32 v149, v149, 0x3e0293ee, v211
	v_exp_f32_e32 v149, v149
	v_fmamk_f32 v150, v150, 0x3e0293ee, v211
	v_add_f32_e32 v212, 0, v146
	v_exp_f32_e32 v150, v150
	v_fmamk_f32 v151, v151, 0x3e0293ee, v211
	v_add_f32_e32 v212, v147, v212
	v_exp_f32_e32 v151, v151
	v_fmamk_f32 v152, v152, 0x3e0293ee, v211
	v_add_f32_e32 v212, v148, v212
	v_exp_f32_e32 v152, v152
	v_fmamk_f32 v153, v153, 0x3e0293ee, v211
	v_add_f32_e32 v212, v149, v212
	v_exp_f32_e32 v153, v153
	v_fmamk_f32 v154, v154, 0x3e0293ee, v211
	v_add_f32_e32 v212, v150, v212
	v_exp_f32_e32 v154, v154
	v_fmamk_f32 v155, v155, 0x3e0293ee, v211
	v_add_f32_e32 v212, v151, v212
	v_exp_f32_e32 v155, v155
	v_fmamk_f32 v156, v156, 0x3e0293ee, v211
	v_add_f32_e32 v212, v152, v212
	v_exp_f32_e32 v156, v156
	v_fmamk_f32 v157, v157, 0x3e0293ee, v211
	v_add_f32_e32 v212, v153, v212
	v_exp_f32_e32 v157, v157
	v_fmamk_f32 v158, v158, 0x3e0293ee, v211
	v_add_f32_e32 v212, v154, v212
	v_exp_f32_e32 v158, v158
	v_fmamk_f32 v159, v159, 0x3e0293ee, v211
	v_add_f32_e32 v212, v155, v212
	v_exp_f32_e32 v159, v159
	v_fmamk_f32 v160, v160, 0x3e0293ee, v211
	v_add_f32_e32 v212, v156, v212
	v_exp_f32_e32 v160, v160
	v_fmac_f32_e32 v211, 0x3e0293ee, v161
	v_add_f32_e32 v212, v157, v212
	v_exp_f32_e32 v161, v211
	v_add_f32_e32 v211, v158, v212
	v_add_f32_e32 v211, v159, v211
	v_add_f32_e32 v211, v160, v211
	v_add_f32_e32 v212, v161, v211
	v_mov_b32_e32 v213, v212
	v_cvt_pk_bf16_f32 v146, v146, v147
	v_cvt_pk_bf16_f32 v147, v148, v149
	v_cvt_pk_bf16_f32 v148, v150, v151
	v_cvt_pk_bf16_f32 v149, v152, v153
	v_cvt_pk_bf16_f32 v150, v154, v155
	v_cvt_pk_bf16_f32 v151, v156, v157
	v_cvt_pk_bf16_f32 v152, v158, v159
	v_cvt_pk_bf16_f32 v153, v160, v161
	s_nop 1
	v_permlane32_swap_b32_e32 v212, v213
	v_permlane32_swap_b32_e32 v146, v148
	v_permlane32_swap_b32_e32 v147, v149
	v_permlane32_swap_b32_e32 v150, v152
	v_permlane32_swap_b32_e32 v151, v153
	s_setprio 1
	s_waitcnt lgkmcnt(0)
	v_mfma_f32_32x32x16_bf16 v[98:113], v[146:149], v[206:209], v[98:113]
	v_lshl_add_u64 v[206:207], s[8:9], 0, v[238:239]
	v_lshl_add_u64 v[154:155], v[206:207], 0, s[92:93]
	s_add_i32 m0, s28, 0x8000
	s_nop 0
	global_load_lds_dwordx4 v[154:155], off
	v_mfma_f32_32x32x16_bf16 v[98:113], v[150:153], v[202:205], v[98:113]
	ds_read_b64_tr_b16 v[154:155], v1 offset:33792
	ds_read_b64_tr_b16 v[156:157], v1 offset:37888
	ds_read_b64_tr_b16 v[158:159], v1 offset:41984
	ds_read_b64_tr_b16 v[160:161], v1 offset:46080
	s_mov_b64 s[4:5], 0xf0000
	v_mfma_f32_32x32x16_bf16 v[114:129], v[146:149], v[198:201], v[114:129]
	v_lshl_add_u64 v[198:199], v[206:207], 0, s[4:5]
	s_add_i32 m0, s28, 0xa000
	s_nop 0
	global_load_lds_dwordx4 v[198:199], off
	v_mfma_f32_32x32x16_bf16 v[114:129], v[150:153], v[194:197], v[114:129]
	ds_read_b64_tr_b16 v[194:195], v1 offset:34304
	ds_read_b64_tr_b16 v[196:197], v1 offset:38400
	ds_read_b64_tr_b16 v[198:199], v1 offset:42496
	ds_read_b64_tr_b16 v[200:201], v1 offset:46592
	s_waitcnt lgkmcnt(4)
	v_mfma_f32_32x32x16_bf16 v[66:81], v[146:149], v[154:157], v[66:81]
	v_lshl_add_u64 v[154:155], v[206:207], 0, s[94:95]
	s_add_i32 m0, s28, 0xc000
	s_nop 0
	global_load_lds_dwordx4 v[154:155], off
	v_mfma_f32_32x32x16_bf16 v[66:81], v[150:153], v[158:161], v[66:81]
	ds_read_b64_tr_b16 v[154:155], v1 offset:34816
	ds_read_b64_tr_b16 v[156:157], v1 offset:38912
	ds_read_b64_tr_b16 v[158:159], v1 offset:43008
	ds_read_b64_tr_b16 v[160:161], v1 offset:47104
	s_mov_b64 s[4:5], 0x150000
	s_waitcnt lgkmcnt(4)
	v_mfma_f32_32x32x16_bf16 v[82:97], v[146:149], v[194:197], v[82:97]
	v_lshl_add_u64 v[194:195], v[206:207], 0, s[4:5]
	s_add_i32 m0, s28, 0xe000
	s_nop 0
	global_load_lds_dwordx4 v[194:195], off
	v_mfma_f32_32x32x16_bf16 v[82:97], v[150:153], v[198:201], v[82:97]
	ds_read_b64_tr_b16 v[194:195], v1 offset:35328
	ds_read_b64_tr_b16 v[196:197], v1 offset:39424
	ds_read_b64_tr_b16 v[198:199], v1 offset:43520
	ds_read_b64_tr_b16 v[200:201], v1 offset:47616
	s_waitcnt lgkmcnt(4)
	v_mfma_f32_32x32x16_bf16 v[34:49], v[146:149], v[154:157], v[34:49]
	v_mfma_f32_32x32x16_bf16 v[34:49], v[150:153], v[158:161], v[34:49]
	ds_read_b64_tr_b16 v[154:155], v1 offset:35840
	ds_read_b64_tr_b16 v[156:157], v1 offset:39936
	ds_read_b64_tr_b16 v[158:159], v1 offset:44032
	ds_read_b64_tr_b16 v[160:161], v1 offset:48128
	s_waitcnt lgkmcnt(4)
	v_mfma_f32_32x32x16_bf16 v[50:65], v[146:149], v[194:197], v[50:65]
	v_mfma_f32_32x32x16_bf16 v[50:65], v[150:153], v[198:201], v[50:65]
	ds_read_b64_tr_b16 v[194:195], v1 offset:36352
	ds_read_b64_tr_b16 v[196:197], v1 offset:40448
	ds_read_b64_tr_b16 v[198:199], v1 offset:44544
	ds_read_b64_tr_b16 v[200:201], v1 offset:48640
	s_waitcnt lgkmcnt(4)
	v_mfma_f32_32x32x16_bf16 v[18:33], v[146:149], v[154:157], v[18:33]
	v_mfma_f32_32x32x16_bf16 v[18:33], v[150:153], v[158:161], v[18:33]
	s_waitcnt lgkmcnt(0)
	v_mfma_f32_32x32x16_bf16 v[2:17], v[146:149], v[194:197], v[2:17]
	v_mfma_f32_32x32x16_bf16 v[2:17], v[150:153], v[198:201], v[2:17]
	s_setprio 0
	ds_read_b64_tr_b16 v[154:155], v1 offset:49152
	ds_read_b64_tr_b16 v[156:157], v1 offset:53248
	ds_read_b64_tr_b16 v[152:153], v1 offset:53760
	ds_read_b64_tr_b16 v[150:151], v1 offset:49664
	ds_read_b64_tr_b16 v[158:159], v1 offset:57344
	ds_read_b64_tr_b16 v[160:161], v1 offset:61440
	ds_read_b64_tr_b16 v[148:149], v1 offset:61952
	ds_read_b64_tr_b16 v[146:147], v1 offset:57856
	s_add_i32 s4, s26, 32
	s_cmpk_lt_i32 s4, 0xff62
	s_cbranch_scc1 .LBB0_558
; __device__ __forceinline__ void softmax_sub(f32x16& p, float& m_reg, float& l_reg, bf16x8& pa0, bf16x8& pa1, f32x16 (&o)[8], float* al_l, int r32, int hi, int dj, const float* tab, float cL, float cR) {
;     ...
;   if (dj <= -159) cb = cL;
;   else if (dj >= 159) cb = cR;
;   else { cb = 0.f; const int ib = dj - r32 + 4 * hi + 128;
; #pragma unroll
;     for (int r = 0; r < 16; ++r) { const int i0 = ib + (r & 3) + 8 * (r >> 2); p[r] += tab[min(max(i0, 0), 256)]; } }
	s_cmpk_gt_i32 s4, 0x9e
	s_cbranch_scc1 .LBB0_559
	v_add_u32_e32 v194, s26, v245
	v_add_u32_e32 v194, 0xa0, v194
	v_mov_b32_e32 v195, 0x100
	v_med3_i32 v195, v194, 0, v195
	v_lshl_add_u32 v202, v195, 2, s20
	v_max_i32_e32 v195, -1, v194
	v_add_u32_e32 v195, 1, v195
	v_min_u32_e32 v195, 0x100, v195
	v_lshl_add_u32 v203, v195, 2, s20
	v_max_i32_e32 v195, -2, v194
	v_add_u32_e32 v195, 2, v195
	v_min_u32_e32 v195, 0x100, v195
	v_lshl_add_u32 v204, v195, 2, s20
	v_max_i32_e32 v195, -3, v194
	v_add_u32_e32 v195, 3, v195
	v_min_u32_e32 v195, 0x100, v195
	v_lshl_add_u32 v205, v195, 2, s20
	v_max_i32_e32 v195, -8, v194
	v_add_u32_e32 v195, 8, v195
	v_min_u32_e32 v195, 0x100, v195
	v_lshl_add_u32 v206, v195, 2, s20
	v_max_i32_e32 v195, -9, v194
	v_add_u32_e32 v195, 9, v195
	v_min_u32_e32 v195, 0x100, v195
	v_lshl_add_u32 v207, v195, 2, s20
	v_max_i32_e32 v195, -10, v194
	v_add_u32_e32 v195, 10, v195
	v_min_u32_e32 v195, 0x100, v195
	v_lshl_add_u32 v208, v195, 2, s20
	v_max_i32_e32 v195, -11, v194
	v_add_u32_e32 v195, 11, v195
	v_min_u32_e32 v195, 0x100, v195
	v_lshl_add_u32 v209, v195, 2, s20
	v_max_i32_e32 v195, -16, v194
	v_max_i32_e32 v196, 0xffffffef, v194
	v_max_i32_e32 v197, 0xffffffee, v194
	v_max_i32_e32 v198, 0xffffffed, v194
	v_max_i32_e32 v199, 0xffffffe8, v194
	v_max_i32_e32 v200, 0xffffffe7, v194
	v_max_i32_e32 v201, 0xffffffe6, v194
	v_add_u32_e32 v195, 16, v195
	v_add_u32_e32 v196, 17, v196
	v_add_u32_e32 v197, 18, v197
	v_add_u32_e32 v198, 19, v198
	v_add_u32_e32 v199, 24, v199
	v_add_u32_e32 v200, 25, v200
	v_add_u32_e32 v201, 26, v201
	v_max_i32_e32 v194, 0xffffffe5, v194
	v_min_u32_e32 v195, 0x100, v195
	v_min_u32_e32 v196, 0x100, v196
	v_min_u32_e32 v197, 0x100, v197
	v_min_u32_e32 v198, 0x100, v198
	v_min_u32_e32 v199, 0x100, v199
	v_min_u32_e32 v200, 0x100, v200
	v_min_u32_e32 v201, 0x100, v201
	v_add_u32_e32 v194, 27, v194
	v_lshl_add_u32 v195, v195, 2, s20
	v_lshl_add_u32 v196, v196, 2, s20
	v_lshl_add_u32 v197, v197, 2, s20
	v_lshl_add_u32 v198, v198, 2, s20
	v_lshl_add_u32 v199, v199, 2, s20
	v_lshl_add_u32 v200, v200, 2, s20
	v_lshl_add_u32 v201, v201, 2, s20
	v_min_u32_e32 v194, 0x100, v194
	v_lshl_add_u32 v211, v194, 2, s20
	ds_read_b32 v194, v195
	ds_read_b32 v195, v196
	ds_read_b32 v196, v197
	ds_read_b32 v197, v198
	ds_read_b32 v198, v199
	ds_read_b32 v199, v200
	ds_read_b32 v200, v201
	ds_read_b32 v201, v211
	ds_read_b32 v202, v202
	ds_read_b32 v203, v203
	ds_read_b32 v204, v204
	ds_read_b32 v205, v205
	ds_read_b32 v206, v206
	ds_read_b32 v207, v207
	ds_read_b32 v208, v208
	ds_read_b32 v209, v209
	s_waitcnt lgkmcnt(0)
	v_pk_add_f32 v[144:145], v[144:145], v[200:201]
	v_pk_add_f32 v[142:143], v[142:143], v[198:199]
	v_pk_add_f32 v[140:141], v[140:141], v[196:197]
	v_pk_add_f32 v[138:139], v[138:139], v[194:195]
	v_pk_add_f32 v[136:137], v[136:137], v[208:209]
	v_pk_add_f32 v[134:135], v[134:135], v[206:207]
	v_pk_add_f32 v[132:133], v[132:133], v[204:205]
	v_pk_add_f32 v[130:131], v[130:131], v[202:203]
	s_mov_b32 s28, 0
	s_branch .LBB0_560

; #define SBAR() __builtin_amdgcn_sched_barrier(0)
; template <int D0, int S> __device__ __forceinline__ VG vload(ldsc_t vb) { VG g; g.l0 = vtr(vb + v_rd_off(D0, 2 * S, 0)); g.h0 = vtr(vb + v_rd_off(D0, 2 * S, 1)); g.l1 = vtr(vb + v_rd_off(D0, 2 * S + 1, 0)); g.h1 = vtr(vb + v_rd_off(D0, 2 * S + 1, 1)); return g; }
; __device__ __forceinline__ void softmax_sub(f32x16& p, float& m_reg, float& l_reg, bf16x8& pa0, bf16x8& pa1, f32x16 (&o)[8], float* al_l, int r32, int hi, int dj, const float* tab, float cL, float cR) {
;     ...
;   const float mnC = (cb - mn) * C;
;   float ps = 0;
; #pragma unroll
;   for (int r = 0; r < 16; ++r) { p[r] = __builtin_amdgcn_exp2f(fmaf(p[r], C, mnC)); ps += p[r]; }
;   { auto rr = __builtin_amdgcn_permlane32_swap(__float_as_uint(ps), __float_as_uint(ps), false, false);
;     ps = __uint_as_float(rr[0]) + __uint_as_float(rr[1]); }
;   l_reg = l_reg * alpha + ps;
;     ...
;   PK4(p, 0, pa0); PK4(p, 8, pa1);
;     ...
; }
; template <int S, class Dma> __device__ __forceinline__ void pv_run(f32x16 (&o)[8], ldsc_t vb, VG g0, VG g1, bf16x8 pa0, bf16x8 pa1, const Dma& dma) {
;   SBAR(); __builtin_amdgcn_s_setprio(1);
;   vmma(o[0], g0, pa0, pa1); dma(0); SBAR(); g0 = vload<2, S>(vb); SBAR();
;   vmma(o[1], g1, pa0, pa1); dma(1); SBAR(); g1 = vload<3, S>(vb); SBAR();
;   vmma(o[2], g0, pa0, pa1); dma(2); SBAR(); g0 = vload<4, S>(vb); SBAR();
;   vmma(o[3], g1, pa0, pa1); dma(3); SBAR(); g1 = vload<5, S>(vb); SBAR();
;   vmma(o[4], g0, pa0, pa1); dma(4); SBAR(); g0 = vload<6, S>(vb); SBAR();
;   vmma(o[5], g1, pa0, pa1); dma(5); SBAR(); g1 = vload<7, S>(vb); SBAR();
;   vmma(o[6], g0, pa0, pa1); dma(6); SBAR(); vmma(o[7], g1, pa0, pa1); dma(7); __builtin_amdgcn_s_setprio(0); SBAR();
.LBB0_562:
	v_sub_f32_e32 v195, s28, v211
	v_mul_f32_e32 v195, 0x3e0293ee, v195
	v_fmamk_f32 v130, v130, 0x3e0293ee, v195
	v_exp_f32_e32 v130, v130
	v_fmamk_f32 v131, v131, 0x3e0293ee, v195
	v_exp_f32_e32 v131, v131
	v_fmamk_f32 v132, v132, 0x3e0293ee, v195
	v_exp_f32_e32 v132, v132
	v_fmamk_f32 v133, v133, 0x3e0293ee, v195
	v_exp_f32_e32 v133, v133
	v_fmamk_f32 v134, v134, 0x3e0293ee, v195
	v_add_f32_e32 v196, 0, v130
	v_exp_f32_e32 v134, v134
	v_fmamk_f32 v135, v135, 0x3e0293ee, v195
	v_add_f32_e32 v196, v131, v196
	v_exp_f32_e32 v135, v135
	v_fmamk_f32 v136, v136, 0x3e0293ee, v195
	v_add_f32_e32 v196, v132, v196
	v_exp_f32_e32 v136, v136
	v_fmamk_f32 v137, v137, 0x3e0293ee, v195
	v_add_f32_e32 v196, v133, v196
	v_exp_f32_e32 v137, v137
	v_fmamk_f32 v138, v138, 0x3e0293ee, v195
	v_add_f32_e32 v196, v134, v196
	v_exp_f32_e32 v138, v138
	v_fmamk_f32 v139, v139, 0x3e0293ee, v195
	v_add_f32_e32 v196, v135, v196
	v_exp_f32_e32 v139, v139
	v_fmamk_f32 v140, v140, 0x3e0293ee, v195
	v_add_f32_e32 v196, v136, v196
	v_exp_f32_e32 v140, v140
	v_fmamk_f32 v141, v141, 0x3e0293ee, v195
	v_add_f32_e32 v196, v137, v196
	v_exp_f32_e32 v141, v141
	v_fmamk_f32 v142, v142, 0x3e0293ee, v195
	v_add_f32_e32 v196, v138, v196
	v_exp_f32_e32 v142, v142
	v_fmamk_f32 v143, v143, 0x3e0293ee, v195
	v_add_f32_e32 v196, v139, v196
	v_exp_f32_e32 v143, v143
	v_fmamk_f32 v144, v144, 0x3e0293ee, v195
	v_add_f32_e32 v196, v140, v196
	v_exp_f32_e32 v144, v144
	v_fmac_f32_e32 v195, 0x3e0293ee, v145
	v_add_f32_e32 v196, v141, v196
	v_exp_f32_e32 v145, v195
	v_add_f32_e32 v195, v142, v196
	v_add_f32_e32 v195, v143, v195
	v_add_f32_e32 v195, v144, v195
	v_add_f32_e32 v195, v145, v195
	v_mov_b32_e32 v196, v195
	v_add_f32_e32 v194, v212, v213
	s_nop 0
	v_permlane32_swap_b32_e32 v195, v196
	v_fmac_f32_e32 v194, v249, v243
	v_add_f32_e32 v249, v195, v196
	s_add_i32 s25, s25, 1
	v_fmac_f32_e32 v249, v194, v214
	v_cvt_pk_bf16_f32 v130, v130, v131
	v_cvt_pk_bf16_f32 v131, v132, v133
	v_cvt_pk_bf16_f32 v132, v134, v135
	v_cvt_pk_bf16_f32 v133, v136, v137
	v_cvt_pk_bf16_f32 v134, v138, v139
	v_cvt_pk_bf16_f32 v135, v140, v141
	v_cvt_pk_bf16_f32 v136, v142, v143
	v_cvt_pk_bf16_f32 v137, v144, v145
	s_nop 0
	v_permlane32_swap_b32_e32 v130, v132
	v_permlane32_swap_b32_e32 v131, v133
	v_permlane32_swap_b32_e32 v134, v136
	v_permlane32_swap_b32_e32 v135, v137
	s_setprio 1
	s_waitcnt lgkmcnt(0)
	v_mfma_f32_32x32x16_bf16 v[98:113], v[130:133], v[154:157], v[98:113]
	v_mfma_f32_32x32x16_bf16 v[98:113], v[134:137], v[158:161], v[98:113]
	ds_read_b64_tr_b16 v[138:139], v1 offset:50176
	ds_read_b64_tr_b16 v[140:141], v1 offset:54272
	ds_read_b64_tr_b16 v[142:143], v1 offset:58368
	ds_read_b64_tr_b16 v[144:145], v1 offset:62464
	v_mfma_f32_32x32x16_bf16 v[114:129], v[130:133], v[150:153], v[114:129]
	v_mfma_f32_32x32x16_bf16 v[114:129], v[134:137], v[146:149], v[114:129]
	ds_read_b64_tr_b16 v[146:147], v1 offset:50688
	ds_read_b64_tr_b16 v[148:149], v1 offset:54784
	ds_read_b64_tr_b16 v[150:151], v1 offset:58880
	ds_read_b64_tr_b16 v[152:153], v1 offset:62976
	s_waitcnt lgkmcnt(4)
	v_mfma_f32_32x32x16_bf16 v[66:81], v[130:133], v[138:141], v[66:81]
	v_mfma_f32_32x32x16_bf16 v[66:81], v[134:137], v[142:145], v[66:81]
	ds_read_b64_tr_b16 v[138:139], v1 offset:51200
	ds_read_b64_tr_b16 v[140:141], v1 offset:55296
	ds_read_b64_tr_b16 v[142:143], v1 offset:59392
	ds_read_b64_tr_b16 v[144:145], v1 offset:63488
	s_waitcnt lgkmcnt(4)
	v_mfma_f32_32x32x16_bf16 v[82:97], v[130:133], v[146:149], v[82:97]
	v_mfma_f32_32x32x16_bf16 v[82:97], v[134:137], v[150:153], v[82:97]
	ds_read_b64_tr_b16 v[146:147], v1 offset:51712
	ds_read_b64_tr_b16 v[148:149], v1 offset:55808
	ds_read_b64_tr_b16 v[150:151], v1 offset:59904
	ds_read_b64_tr_b16 v[152:153], v1 offset:64000
	s_waitcnt lgkmcnt(4)
	v_mfma_f32_32x32x16_bf16 v[34:49], v[130:133], v[138:141], v[34:49]
	v_mfma_f32_32x32x16_bf16 v[34:49], v[134:137], v[142:145], v[34:49]
	ds_read_b64_tr_b16 v[138:139], v1 offset:52224
	ds_read_b64_tr_b16 v[140:141], v1 offset:56320
	ds_read_b64_tr_b16 v[142:143], v1 offset:60416
	ds_read_b64_tr_b16 v[144:145], v1 offset:64512
	s_waitcnt lgkmcnt(4)
	v_mfma_f32_32x32x16_bf16 v[50:65], v[130:133], v[146:149], v[50:65]
	v_mfma_f32_32x32x16_bf16 v[50:65], v[134:137], v[150:153], v[50:65]
	ds_read_b64_tr_b16 v[146:147], v1 offset:52736
	ds_read_b64_tr_b16 v[148:149], v1 offset:56832
	ds_read_b64_tr_b16 v[150:151], v1 offset:60928
	ds_read_b64_tr_b16 v[152:153], v1 offset:65024
	s_waitcnt lgkmcnt(4)
	v_mfma_f32_32x32x16_bf16 v[18:33], v[130:133], v[138:141], v[18:33]
	v_mfma_f32_32x32x16_bf16 v[18:33], v[134:137], v[142:145], v[18:33]
	s_waitcnt lgkmcnt(0)
	v_mfma_f32_32x32x16_bf16 v[2:17], v[130:133], v[146:149], v[2:17]
	v_mfma_f32_32x32x16_bf16 v[2:17], v[134:137], v[150:153], v[2:17]
	s_setprio 0
	s_add_i32 s26, s26, 64
	s_add_i32 s27, s27, 0x10000
	s_add_u32 s8, s8, 0xc0000
	s_addc_u32 s9, s9, 0
	s_cmp_eq_u32 s11, s25
	s_cbranch_scc0 .LBB0_548
	s_branch .LBB0_569

; #define SBAR() __builtin_amdgcn_sched_barrier(0)
; #define KF(a, o) (*(const __attribute__((address_space(3))) bf16x8*)((a) + (o)))
; template <class Hook> __device__ __forceinline__ void qk_sub(f32x16& p, ldsc_t k0, ldsc_t k1, ldsc_t k2, ldsc_t k3, int kd, const bf16x8* qr, const Hook& hook) {
;     ...
;   SBAR();
;   bf16x8 f0 = KF(k0, 0), f1 = KF(k1, 0), f2 = KF(k2, 0), f3 = KF(k3, 0); SBAR(); __builtin_amdgcn_s_setprio(1);
;   p = __builtin_amdgcn_mfma_f32_32x32x16_bf16(f0, qr[0], f32x16{}, 0, 0, 0); f0 = KF(k0 + kd, 0); SBAR();
;   p = __builtin_amdgcn_mfma_f32_32x32x16_bf16(f1, qr[1], p, 0, 0, 0); f1 = KF(k1 + kd, 0); hook(0); SBAR();
;   p = __builtin_amdgcn_mfma_f32_32x32x16_bf16(f2, qr[2], p, 0, 0, 0); f2 = KF(k2 + kd, 0); SBAR();
;   p = __builtin_amdgcn_mfma_f32_32x32x16_bf16(f3, qr[3], p, 0, 0, 0); f3 = KF(k3 + kd, 0); hook(1); SBAR();
;   p = __builtin_amdgcn_mfma_f32_32x32x16_bf16(f0, qr[4], p, 0, 0, 0); SBAR();
;   p = __builtin_amdgcn_mfma_f32_32x32x16_bf16(f1, qr[5], p, 0, 0, 0); hook(2); SBAR();
;   p = __builtin_amdgcn_mfma_f32_32x32x16_bf16(f2, qr[6], p, 0, 0, 0); SBAR();
;   p = __builtin_amdgcn_mfma_f32_32x32x16_bf16(f3, qr[7], p, 0, 0, 0); hook(3); __builtin_amdgcn_s_setprio(0); SBAR();
; __device__ __forceinline__ void softmax_sub(f32x16& p, float& m_reg, float& l_reg, bf16x8& pa0, bf16x8& pa1, f32x16 (&o)[8], float* al_l, int r32, int hi, int dj, const float* tab, float cL, float cR) {
;     ...
;   if (dj <= -159) cb = cL;
;   else if (dj >= 159) cb = cR;
;   else { cb = 0.f; const int ib = dj - r32 + 4 * hi + 128;
; #pragma unroll
;     for (int r = 0; r < 16; ++r) { const int i0 = ib + (r & 3) + 8 * (r >> 2); p[r] += tab[min(max(i0, 0), 256)]; } }
.LBB0_569:
	s_waitcnt vmcnt(0)
	s_barrier
	v_add_u32_e32 v195, 0x80, v245
	v_add_u32_e32 v1, s24, v252
	v_add_u32_e32 v194, s24, v253
	v_add_u32_e32 v200, s24, v241
	v_add_u32_e32 v204, s24, v244
	ds_read_b128 v[130:133], v1
	ds_read_b128 v[134:137], v194
	ds_read_b128 v[138:141], v200
	ds_read_b128 v[142:145], v204
	s_setprio 1
	s_waitcnt lgkmcnt(3)
	v_mfma_f32_32x32x16_bf16 v[146:161], v[130:133], v[190:193], 0
	v_add_u32_e32 v208, v1, v251
	ds_read_b128 v[130:133], v208
	s_waitcnt lgkmcnt(3)
	v_mfma_f32_32x32x16_bf16 v[146:161], v[134:137], v[186:189], v[146:161]
	v_add_u32_e32 v209, v194, v251
	ds_read_b128 v[134:137], v209
	s_waitcnt lgkmcnt(3)
	v_mfma_f32_32x32x16_bf16 v[146:161], v[138:141], v[182:185], v[146:161]
	v_add_u32_e32 v210, v200, v251
	ds_read_b128 v[138:141], v210
	s_waitcnt lgkmcnt(3)
	v_mfma_f32_32x32x16_bf16 v[146:161], v[142:145], v[178:181], v[146:161]
	v_add_u32_e32 v212, v204, v251
	ds_read_b128 v[142:145], v212
	s_waitcnt lgkmcnt(3)
	v_mfma_f32_32x32x16_bf16 v[146:161], v[130:133], v[174:177], v[146:161]
	s_waitcnt lgkmcnt(2)
	v_mfma_f32_32x32x16_bf16 v[146:161], v[134:137], v[170:173], v[146:161]
	s_waitcnt lgkmcnt(1)
	v_mfma_f32_32x32x16_bf16 v[146:161], v[138:141], v[166:169], v[146:161]
	s_waitcnt lgkmcnt(0)
	v_mfma_f32_32x32x16_bf16 v[146:161], v[142:145], v[162:165], v[146:161]
	s_setprio 0
	ds_read_b128 v[130:133], v1 offset:8192
	ds_read_b128 v[196:199], v194 offset:8192
	ds_read_b128 v[200:203], v200 offset:8192
	ds_read_b128 v[204:207], v204 offset:8192
	s_setprio 1
	s_waitcnt lgkmcnt(3)
	v_mfma_f32_32x32x16_bf16 v[130:145], v[130:133], v[190:193], 0
	ds_read_b128 v[190:193], v208 offset:8192
	s_waitcnt lgkmcnt(3)
	v_mfma_f32_32x32x16_bf16 v[130:145], v[196:199], v[186:189], v[130:145]
	ds_read_b128 v[186:189], v209 offset:8192
	s_waitcnt lgkmcnt(3)
	v_mfma_f32_32x32x16_bf16 v[130:145], v[200:203], v[182:185], v[130:145]
	ds_read_b128 v[182:185], v210 offset:8192
	s_waitcnt lgkmcnt(3)
	v_mfma_f32_32x32x16_bf16 v[130:145], v[204:207], v[178:181], v[130:145]
	ds_read_b128 v[178:181], v212 offset:8192
	s_waitcnt lgkmcnt(3)
	v_mfma_f32_32x32x16_bf16 v[130:145], v[190:193], v[174:177], v[130:145]
	s_waitcnt lgkmcnt(2)
	v_mfma_f32_32x32x16_bf16 v[130:145], v[186:189], v[170:173], v[130:145]
	s_waitcnt lgkmcnt(1)
	v_mfma_f32_32x32x16_bf16 v[130:145], v[182:185], v[166:169], v[130:145]
	s_waitcnt lgkmcnt(0)
	v_mfma_f32_32x32x16_bf16 v[130:145], v[178:181], v[162:165], v[130:145]
	s_setprio 0
	v_add_u32_e32 v1, s24, v250
	ds_read_b64_tr_b16 v[170:171], v1 offset:32768
	ds_read_b64_tr_b16 v[172:173], v1 offset:36864
	ds_read_b64_tr_b16 v[168:169], v1 offset:37376
	ds_read_b64_tr_b16 v[166:167], v1 offset:33280
	ds_read_b64_tr_b16 v[174:175], v1 offset:40960
	ds_read_b64_tr_b16 v[176:177], v1 offset:45056
	ds_read_b64_tr_b16 v[164:165], v1 offset:45568
	ds_read_b64_tr_b16 v[162:163], v1 offset:41472
	s_lshl_b32 s8, s11, 6
	s_sub_i32 s4, s8, s21
	s_cmpk_lt_i32 s4, 0xff62
	s_cbranch_scc1 .LBB0_572
	s_cmpk_gt_i32 s4, 0x9e
	v_mov_b32_e32 v244, v240
	v_mov_b32_e32 v245, v0
	v_mov_b64_e32 v[250:251], 0x200
	v_mov_b64_e32 v[252:253], 0x1ff
	s_cbranch_scc1 .LBB0_573
	v_add_u32_e32 v178, s4, v195
	v_mov_b32_e32 v0, 0x100
	v_med3_i32 v179, v178, 0, v0
	v_lshl_add_u32 v186, v179, 2, s20
	v_max_i32_e32 v179, -1, v178
	v_add_u32_e32 v179, 1, v179
	v_min_u32_e32 v179, 0x100, v179
	v_lshl_add_u32 v187, v179, 2, s20
	v_max_i32_e32 v179, -2, v178
	v_add_u32_e32 v179, 2, v179
	v_min_u32_e32 v179, 0x100, v179
	v_lshl_add_u32 v188, v179, 2, s20
	v_max_i32_e32 v179, -3, v178
	v_add_u32_e32 v179, 3, v179
	v_min_u32_e32 v179, 0x100, v179
	v_lshl_add_u32 v189, v179, 2, s20
	v_max_i32_e32 v179, -8, v178
	v_add_u32_e32 v179, 8, v179
	v_min_u32_e32 v179, 0x100, v179
	v_lshl_add_u32 v190, v179, 2, s20
	v_max_i32_e32 v179, -9, v178
	v_add_u32_e32 v179, 9, v179
	v_min_u32_e32 v179, 0x100, v179
	v_lshl_add_u32 v191, v179, 2, s20
	v_max_i32_e32 v179, -10, v178
	v_add_u32_e32 v179, 10, v179
	v_min_u32_e32 v179, 0x100, v179
	v_lshl_add_u32 v192, v179, 2, s20
	v_max_i32_e32 v179, -11, v178
	v_add_u32_e32 v179, 11, v179
	v_min_u32_e32 v179, 0x100, v179
	v_lshl_add_u32 v193, v179, 2, s20
	v_max_i32_e32 v179, -16, v178
	v_max_i32_e32 v180, 0xffffffef, v178
	v_max_i32_e32 v181, 0xffffffee, v178
	v_max_i32_e32 v182, 0xffffffed, v178
	v_max_i32_e32 v183, 0xffffffe8, v178
	v_max_i32_e32 v184, 0xffffffe7, v178
	v_max_i32_e32 v185, 0xffffffe6, v178
	v_add_u32_e32 v179, 16, v179
	v_add_u32_e32 v180, 17, v180
	v_add_u32_e32 v181, 18, v181
	v_add_u32_e32 v182, 19, v182
	v_add_u32_e32 v183, 24, v183
	v_add_u32_e32 v184, 25, v184
	v_add_u32_e32 v185, 26, v185
	v_max_i32_e32 v178, 0xffffffe5, v178
	v_min_u32_e32 v179, 0x100, v179
	v_min_u32_e32 v180, 0x100, v180
	v_min_u32_e32 v181, 0x100, v181
	v_min_u32_e32 v182, 0x100, v182
	v_min_u32_e32 v183, 0x100, v183
	v_min_u32_e32 v184, 0x100, v184
	v_min_u32_e32 v185, 0x100, v185
	v_add_u32_e32 v178, 27, v178
	v_lshl_add_u32 v179, v179, 2, s20
	v_lshl_add_u32 v180, v180, 2, s20
	v_lshl_add_u32 v181, v181, 2, s20
	v_lshl_add_u32 v182, v182, 2, s20
	v_lshl_add_u32 v183, v183, 2, s20
	v_lshl_add_u32 v184, v184, 2, s20
	v_lshl_add_u32 v185, v185, 2, s20
	v_min_u32_e32 v178, 0x100, v178
	v_lshl_add_u32 v194, v178, 2, s20
	ds_read_b32 v178, v179
	ds_read_b32 v179, v180
	ds_read_b32 v180, v181
	ds_read_b32 v181, v182
	ds_read_b32 v182, v183
	ds_read_b32 v183, v184
	ds_read_b32 v184, v185
	ds_read_b32 v185, v194
	ds_read_b32 v186, v186
	ds_read_b32 v187, v187
	ds_read_b32 v188, v188
	ds_read_b32 v189, v189
	ds_read_b32 v190, v190
	ds_read_b32 v191, v191
	ds_read_b32 v192, v192
	ds_read_b32 v193, v193
	s_waitcnt lgkmcnt(0)
	v_pk_add_f32 v[160:161], v[160:161], v[184:185]
	v_pk_add_f32 v[158:159], v[158:159], v[182:183]
	v_pk_add_f32 v[156:157], v[156:157], v[180:181]
	v_pk_add_f32 v[154:155], v[154:155], v[178:179]
	v_pk_add_f32 v[152:153], v[152:153], v[192:193]
	v_pk_add_f32 v[150:151], v[150:151], v[190:191]
	v_pk_add_f32 v[148:149], v[148:149], v[188:189]
	v_pk_add_f32 v[146:147], v[146:147], v[186:187]
	s_mov_b32 s9, 0
	v_mov_b32_e32 v246, 0x260
	s_branch .LBB0_574

; #define SBAR() __builtin_amdgcn_sched_barrier(0)
; template <int D0, int S> __device__ __forceinline__ VG vload(ldsc_t vb) { VG g; g.l0 = vtr(vb + v_rd_off(D0, 2 * S, 0)); g.h0 = vtr(vb + v_rd_off(D0, 2 * S, 1)); g.l1 = vtr(vb + v_rd_off(D0, 2 * S + 1, 0)); g.h1 = vtr(vb + v_rd_off(D0, 2 * S + 1, 1)); return g; }
; __device__ __forceinline__ void softmax_sub(f32x16& p, float& m_reg, float& l_reg, bf16x8& pa0, bf16x8& pa1, f32x16 (&o)[8], float* al_l, int r32, int hi, int dj, const float* tab, float cL, float cR) {
;     ...
;   const float mnC = (cb - mn) * C;
;   float ps = 0;
; #pragma unroll
;   for (int r = 0; r < 16; ++r) { p[r] = __builtin_amdgcn_exp2f(fmaf(p[r], C, mnC)); ps += p[r]; }
;   { auto rr = __builtin_amdgcn_permlane32_swap(__float_as_uint(ps), __float_as_uint(ps), false, false);
;     ps = __uint_as_float(rr[0]) + __uint_as_float(rr[1]); }
;   l_reg = l_reg * alpha + ps;
;     ...
;   PK4(p, 0, pa0); PK4(p, 8, pa1);
;     ...
; }
; template <int S, class Dma> __device__ __forceinline__ void pv_run(f32x16 (&o)[8], ldsc_t vb, VG g0, VG g1, bf16x8 pa0, bf16x8 pa1, const Dma& dma) {
;   SBAR(); __builtin_amdgcn_s_setprio(1);
;   vmma(o[0], g0, pa0, pa1); dma(0); SBAR(); g0 = vload<2, S>(vb); SBAR();
;   vmma(o[1], g1, pa0, pa1); dma(1); SBAR(); g1 = vload<3, S>(vb); SBAR();
;   vmma(o[2], g0, pa0, pa1); dma(2); SBAR(); g0 = vload<4, S>(vb); SBAR();
;   vmma(o[3], g1, pa0, pa1); dma(3); SBAR(); g1 = vload<5, S>(vb); SBAR();
;   vmma(o[4], g0, pa0, pa1); dma(4); SBAR(); g0 = vload<6, S>(vb); SBAR();
;   vmma(o[5], g1, pa0, pa1); dma(5); SBAR(); g1 = vload<7, S>(vb); SBAR();
;   vmma(o[6], g0, pa0, pa1); dma(6); SBAR(); vmma(o[7], g1, pa0, pa1); dma(7); __builtin_amdgcn_s_setprio(0); SBAR();
.LBB0_576:
	v_sub_f32_e32 v178, s9, v196
	v_mul_f32_e32 v178, 0x3e0293ee, v178
	v_fmamk_f32 v146, v146, 0x3e0293ee, v178
	v_exp_f32_e32 v146, v146
	v_fmamk_f32 v147, v147, 0x3e0293ee, v178
	v_exp_f32_e32 v147, v147
	v_fmamk_f32 v148, v148, 0x3e0293ee, v178
	v_exp_f32_e32 v148, v148
	v_fmamk_f32 v149, v149, 0x3e0293ee, v178
	v_exp_f32_e32 v149, v149
	v_fmamk_f32 v150, v150, 0x3e0293ee, v178
	v_add_f32_e32 v179, 0, v146
	v_exp_f32_e32 v150, v150
	v_fmamk_f32 v151, v151, 0x3e0293ee, v178
	v_add_f32_e32 v179, v147, v179
	v_exp_f32_e32 v151, v151
	v_fmamk_f32 v152, v152, 0x3e0293ee, v178
	v_add_f32_e32 v179, v148, v179
	v_exp_f32_e32 v152, v152
	v_fmamk_f32 v153, v153, 0x3e0293ee, v178
	v_add_f32_e32 v179, v149, v179
	v_exp_f32_e32 v153, v153
	v_fmamk_f32 v154, v154, 0x3e0293ee, v178
	v_add_f32_e32 v179, v150, v179
	v_exp_f32_e32 v154, v154
	v_fmamk_f32 v155, v155, 0x3e0293ee, v178
	v_add_f32_e32 v179, v151, v179
	v_exp_f32_e32 v155, v155
	v_fmamk_f32 v156, v156, 0x3e0293ee, v178
	v_add_f32_e32 v179, v152, v179
	v_exp_f32_e32 v156, v156
	v_fmamk_f32 v157, v157, 0x3e0293ee, v178
	v_add_f32_e32 v179, v153, v179
	v_exp_f32_e32 v157, v157
	v_fmamk_f32 v158, v158, 0x3e0293ee, v178
	v_add_f32_e32 v179, v154, v179
	v_exp_f32_e32 v158, v158
	v_fmamk_f32 v159, v159, 0x3e0293ee, v178
	v_add_f32_e32 v179, v155, v179
	v_exp_f32_e32 v159, v159
	v_fmamk_f32 v160, v160, 0x3e0293ee, v178
	v_add_f32_e32 v179, v156, v179
	v_exp_f32_e32 v160, v160
	v_fmac_f32_e32 v178, 0x3e0293ee, v161
	v_add_f32_e32 v179, v157, v179
	v_exp_f32_e32 v161, v178
	v_add_f32_e32 v178, v158, v179
	v_add_f32_e32 v178, v159, v178
	v_add_f32_e32 v178, v160, v178
	v_add_f32_e32 v178, v161, v178
	v_mov_b32_e32 v179, v178
	v_cvt_pk_bf16_f32 v146, v146, v147
	v_cvt_pk_bf16_f32 v147, v148, v149
	v_cvt_pk_bf16_f32 v148, v150, v151
	v_cvt_pk_bf16_f32 v149, v152, v153
	v_cvt_pk_bf16_f32 v150, v154, v155
	v_cvt_pk_bf16_f32 v151, v156, v157
	v_cvt_pk_bf16_f32 v152, v158, v159
	v_cvt_pk_bf16_f32 v153, v160, v161
	s_nop 1
	v_permlane32_swap_b32_e32 v178, v179
	v_permlane32_swap_b32_e32 v146, v148
	v_permlane32_swap_b32_e32 v147, v149
	v_permlane32_swap_b32_e32 v150, v152
	v_permlane32_swap_b32_e32 v151, v153
	s_setprio 1
	s_waitcnt lgkmcnt(0)
	v_mfma_f32_32x32x16_bf16 v[98:113], v[146:149], v[170:173], v[98:113]
	v_mfma_f32_32x32x16_bf16 v[98:113], v[150:153], v[174:177], v[98:113]
	ds_read_b64_tr_b16 v[154:155], v1 offset:33792
	ds_read_b64_tr_b16 v[156:157], v1 offset:37888
	ds_read_b64_tr_b16 v[158:159], v1 offset:41984
	ds_read_b64_tr_b16 v[160:161], v1 offset:46080
	v_mfma_f32_32x32x16_bf16 v[114:129], v[146:149], v[166:169], v[114:129]
	v_mfma_f32_32x32x16_bf16 v[114:129], v[150:153], v[162:165], v[114:129]
	ds_read_b64_tr_b16 v[162:163], v1 offset:34304
	ds_read_b64_tr_b16 v[164:165], v1 offset:38400
	ds_read_b64_tr_b16 v[166:167], v1 offset:42496
	ds_read_b64_tr_b16 v[168:169], v1 offset:46592
	s_waitcnt lgkmcnt(4)
	v_mfma_f32_32x32x16_bf16 v[66:81], v[146:149], v[154:157], v[66:81]
	v_mfma_f32_32x32x16_bf16 v[66:81], v[150:153], v[158:161], v[66:81]
	ds_read_b64_tr_b16 v[154:155], v1 offset:34816
	ds_read_b64_tr_b16 v[156:157], v1 offset:38912
	ds_read_b64_tr_b16 v[158:159], v1 offset:43008
	ds_read_b64_tr_b16 v[160:161], v1 offset:47104
	s_waitcnt lgkmcnt(4)
	v_mfma_f32_32x32x16_bf16 v[82:97], v[146:149], v[162:165], v[82:97]
	v_mfma_f32_32x32x16_bf16 v[82:97], v[150:153], v[166:169], v[82:97]
	ds_read_b64_tr_b16 v[162:163], v1 offset:35328
	ds_read_b64_tr_b16 v[164:165], v1 offset:39424
	ds_read_b64_tr_b16 v[166:167], v1 offset:43520
	ds_read_b64_tr_b16 v[168:169], v1 offset:47616
	s_waitcnt lgkmcnt(4)
	v_mfma_f32_32x32x16_bf16 v[34:49], v[146:149], v[154:157], v[34:49]
	v_mfma_f32_32x32x16_bf16 v[34:49], v[150:153], v[158:161], v[34:49]
	ds_read_b64_tr_b16 v[154:155], v1 offset:35840
	ds_read_b64_tr_b16 v[156:157], v1 offset:39936
	ds_read_b64_tr_b16 v[158:159], v1 offset:44032
	ds_read_b64_tr_b16 v[160:161], v1 offset:48128
	s_waitcnt lgkmcnt(4)
	v_mfma_f32_32x32x16_bf16 v[50:65], v[146:149], v[162:165], v[50:65]
	v_mfma_f32_32x32x16_bf16 v[50:65], v[150:153], v[166:169], v[50:65]
	ds_read_b64_tr_b16 v[162:163], v1 offset:36352
	ds_read_b64_tr_b16 v[164:165], v1 offset:40448
	ds_read_b64_tr_b16 v[166:167], v1 offset:44544
	ds_read_b64_tr_b16 v[168:169], v1 offset:48640
	s_waitcnt lgkmcnt(4)
	v_mfma_f32_32x32x16_bf16 v[18:33], v[146:149], v[154:157], v[18:33]
	v_mfma_f32_32x32x16_bf16 v[18:33], v[150:153], v[158:161], v[18:33]
	s_waitcnt lgkmcnt(0)
	v_mfma_f32_32x32x16_bf16 v[2:17], v[146:149], v[162:165], v[2:17]
	v_mfma_f32_32x32x16_bf16 v[2:17], v[150:153], v[166:169], v[2:17]
	s_setprio 0
	ds_read_b64_tr_b16 v[154:155], v1 offset:49152
	ds_read_b64_tr_b16 v[156:157], v1 offset:53248
	ds_read_b64_tr_b16 v[152:153], v1 offset:53760
	ds_read_b64_tr_b16 v[150:151], v1 offset:49664
	ds_read_b64_tr_b16 v[158:159], v1 offset:57344
	ds_read_b64_tr_b16 v[160:161], v1 offset:61440
	ds_read_b64_tr_b16 v[148:149], v1 offset:61952
	ds_read_b64_tr_b16 v[146:147], v1 offset:57856
	s_or_b32 s4, s8, 32
	s_sub_i32 s4, s4, s21
	s_cmpk_lt_i32 s4, 0xff62
	s_cbranch_scc1 .LBB0_580
; __device__ __forceinline__ void softmax_sub(f32x16& p, float& m_reg, float& l_reg, bf16x8& pa0, bf16x8& pa1, f32x16 (&o)[8], float* al_l, int r32, int hi, int dj, const float* tab, float cL, float cR) {
;     ...
;   if (dj <= -159) cb = cL;
;   else if (dj >= 159) cb = cR;
;   else { cb = 0.f; const int ib = dj - r32 + 4 * hi + 128;
; #pragma unroll
;     for (int r = 0; r < 16; ++r) { const int i0 = ib + (r & 3) + 8 * (r >> 2); p[r] += tab[min(max(i0, 0), 256)]; } }
	s_cmpk_gt_i32 s4, 0x9e
	s_cbranch_scc1 .LBB0_579
	v_add_u32_e32 v162, s4, v195
	v_mov_b32_e32 v0, 0x100
	v_med3_i32 v163, v162, 0, v0
	v_lshl_add_u32 v170, v163, 2, s20
	v_max_i32_e32 v163, -1, v162
	v_add_u32_e32 v163, 1, v163
	v_min_u32_e32 v163, 0x100, v163
	v_lshl_add_u32 v171, v163, 2, s20
	v_max_i32_e32 v163, -2, v162
	v_add_u32_e32 v163, 2, v163
	v_min_u32_e32 v163, 0x100, v163
	v_lshl_add_u32 v172, v163, 2, s20
	v_max_i32_e32 v163, -3, v162
	v_add_u32_e32 v163, 3, v163
	v_min_u32_e32 v163, 0x100, v163
	v_lshl_add_u32 v173, v163, 2, s20
	v_max_i32_e32 v163, -8, v162
	v_add_u32_e32 v163, 8, v163
	v_min_u32_e32 v163, 0x100, v163
	v_lshl_add_u32 v174, v163, 2, s20
	v_max_i32_e32 v163, -9, v162
	v_add_u32_e32 v163, 9, v163
	v_min_u32_e32 v163, 0x100, v163
	v_lshl_add_u32 v175, v163, 2, s20
	v_max_i32_e32 v163, -10, v162
	v_add_u32_e32 v163, 10, v163
	v_min_u32_e32 v163, 0x100, v163
	v_lshl_add_u32 v176, v163, 2, s20
	v_max_i32_e32 v163, -11, v162
	v_add_u32_e32 v163, 11, v163
	v_min_u32_e32 v163, 0x100, v163
	v_lshl_add_u32 v177, v163, 2, s20
	v_max_i32_e32 v163, -16, v162
	v_max_i32_e32 v164, 0xffffffef, v162
	v_max_i32_e32 v165, 0xffffffee, v162
	v_max_i32_e32 v166, 0xffffffed, v162
	v_max_i32_e32 v167, 0xffffffe8, v162
	v_max_i32_e32 v168, 0xffffffe7, v162
	v_max_i32_e32 v169, 0xffffffe6, v162
	v_add_u32_e32 v163, 16, v163
	v_add_u32_e32 v164, 17, v164
	v_add_u32_e32 v165, 18, v165
	v_add_u32_e32 v166, 19, v166
	v_add_u32_e32 v167, 24, v167
	v_add_u32_e32 v168, 25, v168
	v_add_u32_e32 v169, 26, v169
	v_max_i32_e32 v162, 0xffffffe5, v162
	v_min_u32_e32 v163, 0x100, v163
	v_min_u32_e32 v164, 0x100, v164
	v_min_u32_e32 v165, 0x100, v165
	v_min_u32_e32 v166, 0x100, v166
	v_min_u32_e32 v167, 0x100, v167
	v_min_u32_e32 v168, 0x100, v168
	v_min_u32_e32 v169, 0x100, v169
	v_add_u32_e32 v162, 27, v162
	v_lshl_add_u32 v163, v163, 2, s20
	v_lshl_add_u32 v164, v164, 2, s20
	v_lshl_add_u32 v165, v165, 2, s20
	v_lshl_add_u32 v166, v166, 2, s20
	v_lshl_add_u32 v167, v167, 2, s20
	v_lshl_add_u32 v168, v168, 2, s20
	v_lshl_add_u32 v169, v169, 2, s20
	v_min_u32_e32 v162, 0x100, v162
	v_lshl_add_u32 v180, v162, 2, s20
	ds_read_b32 v162, v163
	ds_read_b32 v163, v164
	ds_read_b32 v164, v165
	ds_read_b32 v165, v166
	ds_read_b32 v166, v167
	ds_read_b32 v167, v168
	ds_read_b32 v168, v169
	ds_read_b32 v169, v180
	ds_read_b32 v170, v170
	ds_read_b32 v171, v171
	ds_read_b32 v172, v172
	ds_read_b32 v173, v173
	ds_read_b32 v174, v174
	ds_read_b32 v175, v175
	ds_read_b32 v176, v176
	ds_read_b32 v177, v177
	s_waitcnt lgkmcnt(0)
	v_pk_add_f32 v[144:145], v[144:145], v[168:169]
	v_pk_add_f32 v[142:143], v[142:143], v[166:167]
	v_pk_add_f32 v[140:141], v[140:141], v[164:165]
	v_pk_add_f32 v[138:139], v[138:139], v[162:163]
	v_pk_add_f32 v[136:137], v[136:137], v[176:177]
	v_pk_add_f32 v[134:135], v[134:135], v[174:175]
	v_pk_add_f32 v[132:133], v[132:133], v[172:173]
	v_pk_add_f32 v[130:131], v[130:131], v[170:171]
	s_mov_b32 s22, 0

; #define SBAR() __builtin_amdgcn_sched_barrier(0)
; __device__ __forceinline__ int crow(int r, int hi) { return (r & 3) + 8 * (r >> 2) + 4 * hi; }
; template <int D0, int S> __device__ __forceinline__ VG vload(ldsc_t vb) { VG g; g.l0 = vtr(vb + v_rd_off(D0, 2 * S, 0)); g.h0 = vtr(vb + v_rd_off(D0, 2 * S, 1)); g.l1 = vtr(vb + v_rd_off(D0, 2 * S + 1, 0)); g.h1 = vtr(vb + v_rd_off(D0, 2 * S + 1, 1)); return g; }
; __device__ __forceinline__ void softmax_sub(f32x16& p, float& m_reg, float& l_reg, bf16x8& pa0, bf16x8& pa1, f32x16 (&o)[8], float* al_l, int r32, int hi, int dj, const float* tab, float cL, float cR) {
;     ...
;   const float mnC = (cb - mn) * C;
;   float ps = 0;
; #pragma unroll
;   for (int r = 0; r < 16; ++r) { p[r] = __builtin_amdgcn_exp2f(fmaf(p[r], C, mnC)); ps += p[r]; }
;   { auto rr = __builtin_amdgcn_permlane32_swap(__float_as_uint(ps), __float_as_uint(ps), false, false);
;     ps = __uint_as_float(rr[0]) + __uint_as_float(rr[1]); }
;   l_reg = l_reg * alpha + ps;
;     ...
;   PK4(p, 0, pa0); PK4(p, 8, pa1);
;     ...
; }
; template <int S, class Dma> __device__ __forceinline__ void pv_run(f32x16 (&o)[8], ldsc_t vb, VG g0, VG g1, bf16x8 pa0, bf16x8 pa1, const Dma& dma) {
;   SBAR(); __builtin_amdgcn_s_setprio(1);
;   vmma(o[0], g0, pa0, pa1); dma(0); SBAR(); g0 = vload<2, S>(vb); SBAR();
;   vmma(o[1], g1, pa0, pa1); dma(1); SBAR(); g1 = vload<3, S>(vb); SBAR();
;   vmma(o[2], g0, pa0, pa1); dma(2); SBAR(); g0 = vload<4, S>(vb); SBAR();
;   vmma(o[3], g1, pa0, pa1); dma(3); SBAR(); g1 = vload<5, S>(vb); SBAR();
;   vmma(o[4], g0, pa0, pa1); dma(4); SBAR(); g0 = vload<6, S>(vb); SBAR();
;   vmma(o[5], g1, pa0, pa1); dma(5); SBAR(); g1 = vload<7, S>(vb); SBAR();
;   vmma(o[6], g0, pa0, pa1); dma(6); SBAR(); vmma(o[7], g1, pa0, pa1); dma(7); __builtin_amdgcn_s_setprio(0); SBAR();
; __device__ __forceinline__ void attn_unit(const bf16* __restrict__ qkvb, int seq, int q0, int h, ldsp_t ldsb, float* wsc, const float* tab, float lam) {
;     ...
;   if (hi == 0) li_l[r32] = l_reg; asm volatile("s_waitcnt lgkmcnt(0)" ::: "memory");
;   float rli[16];
; #pragma unroll
;   for (int r = 0; r < 16; ++r) rli[r] = __builtin_amdgcn_rcpf(li_l[crow(r, hi)]);
.LBB0_582:
	v_sub_f32_e32 v162, s19, v181
	v_mul_f32_e32 v162, 0x3e0293ee, v162
	v_fmamk_f32 v130, v130, 0x3e0293ee, v162
	v_exp_f32_e32 v163, v130
	v_fmamk_f32 v130, v131, 0x3e0293ee, v162
	v_exp_f32_e32 v164, v130
	v_fmamk_f32 v130, v132, 0x3e0293ee, v162
	v_exp_f32_e32 v165, v130
	v_fmamk_f32 v130, v133, 0x3e0293ee, v162
	v_exp_f32_e32 v133, v130
	v_fmamk_f32 v131, v134, 0x3e0293ee, v162
	v_add_f32_e32 v130, 0, v163
	v_exp_f32_e32 v134, v131
	v_fmamk_f32 v131, v135, 0x3e0293ee, v162
	v_add_f32_e32 v130, v164, v130
	v_exp_f32_e32 v135, v131
	v_fmamk_f32 v131, v136, 0x3e0293ee, v162
	v_add_f32_e32 v130, v165, v130
	v_exp_f32_e32 v136, v131
	v_fmamk_f32 v131, v137, 0x3e0293ee, v162
	v_add_f32_e32 v130, v133, v130
	v_exp_f32_e32 v137, v131
	v_fmamk_f32 v131, v138, 0x3e0293ee, v162
	v_add_f32_e32 v130, v134, v130
	v_exp_f32_e32 v138, v131
	v_fmamk_f32 v131, v139, 0x3e0293ee, v162
	v_add_f32_e32 v130, v135, v130
	v_exp_f32_e32 v139, v131
	v_fmamk_f32 v131, v140, 0x3e0293ee, v162
	v_add_f32_e32 v130, v136, v130
	v_exp_f32_e32 v140, v131
	v_fmamk_f32 v131, v141, 0x3e0293ee, v162
	v_add_f32_e32 v130, v137, v130
	v_exp_f32_e32 v141, v131
	v_fmamk_f32 v131, v142, 0x3e0293ee, v162
	v_add_f32_e32 v130, v138, v130
	v_exp_f32_e32 v142, v131
	v_fmamk_f32 v131, v143, 0x3e0293ee, v162
	v_add_f32_e32 v130, v139, v130
	v_exp_f32_e32 v143, v131
	v_fmamk_f32 v131, v144, 0x3e0293ee, v162
	v_add_f32_e32 v130, v140, v130
	v_exp_f32_e32 v144, v131
	v_fmac_f32_e32 v162, 0x3e0293ee, v145
	v_add_f32_e32 v130, v141, v130
	v_exp_f32_e32 v145, v162
	v_add_f32_e32 v130, v142, v130
	v_add_f32_e32 v130, v143, v130
	v_add_f32_e32 v130, v144, v130
	v_add_f32_e32 v130, v145, v130
	v_mov_b32_e32 v131, v130
	s_nop 1
	v_permlane32_swap_b32_e32 v130, v131
	v_cvt_pk_bf16_f32 v132, v163, v164
	v_cvt_pk_bf16_f32 v133, v165, v133
	v_cvt_pk_bf16_f32 v134, v134, v135
	v_cvt_pk_bf16_f32 v135, v136, v137
	v_cvt_pk_bf16_f32 v136, v138, v139
	v_cvt_pk_bf16_f32 v137, v140, v141
	v_cvt_pk_bf16_f32 v138, v142, v143
	v_cvt_pk_bf16_f32 v139, v144, v145
	s_nop 0
	v_permlane32_swap_b32_e32 v132, v134
	v_permlane32_swap_b32_e32 v133, v135
	v_permlane32_swap_b32_e32 v136, v138
	v_permlane32_swap_b32_e32 v137, v139
	s_setprio 1
	s_waitcnt lgkmcnt(0)
	v_mfma_f32_32x32x16_bf16 v[98:113], v[132:135], v[154:157], v[98:113]
	v_mfma_f32_32x32x16_bf16 v[98:113], v[136:139], v[158:161], v[98:113]
	ds_read_b64_tr_b16 v[140:141], v1 offset:50176
	ds_read_b64_tr_b16 v[142:143], v1 offset:54272
	ds_read_b64_tr_b16 v[154:155], v1 offset:58368
	ds_read_b64_tr_b16 v[156:157], v1 offset:62464
	v_mfma_f32_32x32x16_bf16 v[114:129], v[132:135], v[150:153], v[114:129]
	v_mfma_f32_32x32x16_bf16 v[114:129], v[136:139], v[146:149], v[114:129]
	ds_read_b64_tr_b16 v[144:145], v1 offset:50688
	ds_read_b64_tr_b16 v[146:147], v1 offset:54784
	ds_read_b64_tr_b16 v[148:149], v1 offset:58880
	ds_read_b64_tr_b16 v[150:151], v1 offset:62976
	s_waitcnt lgkmcnt(4)
	v_mfma_f32_32x32x16_bf16 v[66:81], v[132:135], v[140:143], v[66:81]
	v_mfma_f32_32x32x16_bf16 v[66:81], v[136:139], v[154:157], v[66:81]
	ds_read_b64_tr_b16 v[140:141], v1 offset:51200
	ds_read_b64_tr_b16 v[142:143], v1 offset:55296
	ds_read_b64_tr_b16 v[152:153], v1 offset:59392
	ds_read_b64_tr_b16 v[154:155], v1 offset:63488
	s_waitcnt lgkmcnt(4)
	v_mfma_f32_32x32x16_bf16 v[82:97], v[132:135], v[144:147], v[82:97]
	v_mfma_f32_32x32x16_bf16 v[82:97], v[136:139], v[148:151], v[82:97]
	ds_read_b64_tr_b16 v[144:145], v1 offset:51712
	ds_read_b64_tr_b16 v[146:147], v1 offset:55808
	ds_read_b64_tr_b16 v[148:149], v1 offset:59904
	ds_read_b64_tr_b16 v[150:151], v1 offset:64000
	s_waitcnt lgkmcnt(4)
	v_mfma_f32_32x32x16_bf16 v[34:49], v[132:135], v[140:143], v[34:49]
	v_mfma_f32_32x32x16_bf16 v[34:49], v[136:139], v[152:155], v[34:49]
	ds_read_b64_tr_b16 v[140:141], v1 offset:52224
	ds_read_b64_tr_b16 v[142:143], v1 offset:56320
	ds_read_b64_tr_b16 v[152:153], v1 offset:60416
	ds_read_b64_tr_b16 v[154:155], v1 offset:64512
	s_waitcnt lgkmcnt(4)
	v_mfma_f32_32x32x16_bf16 v[50:65], v[132:135], v[144:147], v[50:65]
	v_mfma_f32_32x32x16_bf16 v[50:65], v[136:139], v[148:151], v[50:65]
	ds_read_b64_tr_b16 v[144:145], v1 offset:52736
	ds_read_b64_tr_b16 v[146:147], v1 offset:56832
	ds_read_b64_tr_b16 v[148:149], v1 offset:60928
	ds_read_b64_tr_b16 v[150:151], v1 offset:65024
	s_waitcnt lgkmcnt(4)
	v_mfma_f32_32x32x16_bf16 v[18:33], v[132:135], v[140:143], v[18:33]
	v_mfma_f32_32x32x16_bf16 v[18:33], v[136:139], v[152:155], v[18:33]
	s_waitcnt lgkmcnt(0)
	v_mfma_f32_32x32x16_bf16 v[2:17], v[132:135], v[144:147], v[2:17]
	v_mfma_f32_32x32x16_bf16 v[2:17], v[136:139], v[148:151], v[2:17]
	s_setprio 0
	s_and_saveexec_b64 s[4:5], vcc
	v_add_f32_e32 v1, v178, v179
	v_fmac_f32_e32 v1, v249, v194
	v_add_f32_e32 v130, v130, v131
	v_fmac_f32_e32 v130, v1, v180
	ds_write_b32 v237, v130
	s_or_b64 exec, exec, s[4:5]
	s_waitcnt lgkmcnt(0)
	v_add_u32_e32 v1, s18, v236
	ds_read_b128 v[130:133], v1
	ds_read_b128 v[134:137], v1 offset:32
	s_lshl_b32 s4, s17, 10
	s_add_i32 s4, s4, 0
	s_cmpk_lt_u32 s16, 0x100
	s_waitcnt lgkmcnt(0)
	v_rcp_f32_e32 v158, v130
	v_rcp_f32_e32 v156, v131
	v_rcp_f32_e32 v155, v132
	v_rcp_f32_e32 v153, v133
	v_rcp_f32_e32 v152, v134
	ds_read_b128 v[130:133], v1 offset:64
	v_rcp_f32_e32 v150, v135
	v_rcp_f32_e32 v149, v136
	v_rcp_f32_e32 v147, v137
	ds_read_b128 v[134:137], v1 offset:96
	s_waitcnt lgkmcnt(0)
	v_rcp_f32_e32 v146, v130
	v_rcp_f32_e32 v144, v131
	v_rcp_f32_e32 v143, v132
	v_rcp_f32_e32 v142, v133
	v_rcp_f32_e32 v141, v134
	v_rcp_f32_e32 v139, v135
	v_rcp_f32_e32 v134, v136
	v_rcp_f32_e32 v130, v137
	v_lshl_add_u32 v1, v248, 12, s4
	s_waitcnt lgkmcnt(0)
	s_barrier
; __device__ __forceinline__ void attn_unit(const bf16* __restrict__ qkvb, int seq, int q0, int h, ldsp_t ldsb, float* wsc, const float* tab, float lam) {
;     ...
;   if (mapw) {
; #pragma unroll
;     for (int r = 0; r < 16; ++r)
; #pragma unroll
;       for (int d = 0; d < 8; ++d) df[((r & 3) + 8 * (r >> 2)) * 256 + ((d * 32 + r32) ^ ((d >> 1) << 2) ^ ((r & 3) << 4))] = -lam * o[d][r] * rli[r];
;   }
	s_cselect_b64 s[4:5], -1, 0
	v_lshl_add_u32 v159, v247, 2, v1
	v_xor_b32_e32 v131, 4, v247
	v_xor_b32_e32 v132, 8, v247
	v_xor_b32_e32 v133, 12, v247
	v_xor_b32_e32 v135, 16, v247
	v_xor_b32_e32 v140, 20, v247
	v_xor_b32_e32 v145, 24, v247
	v_xor_b32_e32 v148, 28, v247
	s_and_b64 vcc, exec, s[4:5]
	v_lshl_add_u32 v138, v131, 2, v1
	v_lshl_add_u32 v137, v132, 2, v1
	v_lshl_add_u32 v136, v133, 2, v1
	v_lshl_add_u32 v135, v135, 2, v1
	v_lshl_add_u32 v133, v140, 2, v1
	v_lshl_add_u32 v132, v145, 2, v1
	v_lshl_add_u32 v131, v148, 2, v1
	v_add_u32_e32 v157, 0x800, v159
	v_add_u32_e32 v154, 0x2000, v159
	v_add_u32_e32 v151, 0x2800, v159
	v_add_u32_e32 v148, 0x4000, v159
	v_add_u32_e32 v145, 0x4800, v159
	v_add_u32_e32 v1, 0x6000, v159
	v_add_u32_e32 v140, 0x6800, v159
	s_cbranch_vccnz .LBB0_586
	v_mul_f32_e64 v160, v98, -s12
	v_mul_f32_e64 v161, v114, -s12
	v_mul_f32_e32 v160, v160, v158
	v_mul_f32_e32 v161, v161, v158
	ds_write2_b32 v159, v160, v161 offset1:32
	v_mul_f32_e64 v160, v66, -s12
	v_mul_f32_e64 v161, v82, -s12
	v_mul_f32_e32 v160, v160, v158
	v_mul_f32_e32 v161, v161, v158
	ds_write2_b32 v138, v160, v161 offset0:64 offset1:96
	v_mul_f32_e64 v160, v34, -s12
	v_mul_f32_e64 v161, v50, -s12
	v_mul_f32_e32 v160, v160, v158
	v_mul_f32_e32 v161, v161, v158
	ds_write2_b32 v137, v160, v161 offset0:128 offset1:160
	v_mul_f32_e64 v160, v18, -s12
	v_mul_f32_e64 v161, v2, -s12
	v_mul_f32_e32 v160, v160, v158
	v_mul_f32_e32 v161, v161, v158
	ds_write2_b32 v136, v160, v161 offset0:192 offset1:224
	v_mul_f32_e64 v160, v99, -s12
	v_mul_f32_e64 v161, v115, -s12
	v_mul_f32_e32 v160, v160, v156
	v_mul_f32_e32 v161, v161, v156
	v_add_u32_e32 v162, 0x400, v135
	ds_write2_b32 v162, v160, v161 offset1:32
	v_mul_f32_e64 v160, v67, -s12
	v_mul_f32_e64 v161, v83, -s12
	v_mul_f32_e32 v160, v160, v156
	v_mul_f32_e32 v161, v161, v156
	v_add_u32_e32 v162, 0x400, v133
	ds_write2_b32 v162, v160, v161 offset0:64 offset1:96
	v_mul_f32_e64 v160, v35, -s12
	v_mul_f32_e64 v161, v51, -s12
	v_mul_f32_e32 v160, v160, v156
	v_mul_f32_e32 v161, v161, v156
	v_add_u32_e32 v162, 0x400, v132
	ds_write2_b32 v162, v160, v161 offset0:128 offset1:160
	v_mul_f32_e64 v160, v19, -s12
	v_mul_f32_e64 v161, v3, -s12
	v_mul_f32_e32 v160, v160, v156
	v_mul_f32_e32 v161, v161, v156
	v_add_u32_e32 v162, 0x400, v131
	ds_write2_b32 v162, v160, v161 offset0:192 offset1:224
	v_mul_f32_e64 v160, v100, -s12
	v_mul_f32_e64 v161, v116, -s12
	v_mul_f32_e32 v160, v160, v155
	v_mul_f32_e32 v161, v161, v155
	ds_write2_b32 v157, v161, v160 offset1:32
	v_mul_f32_e64 v160, v68, -s12
	v_mul_f32_e64 v161, v84, -s12
	v_mul_f32_e32 v160, v160, v155
	v_mul_f32_e32 v161, v161, v155
	v_add_u32_e32 v162, 0x800, v138
	ds_write2_b32 v162, v161, v160 offset0:64 offset1:96
	v_mul_f32_e64 v160, v36, -s12
	v_mul_f32_e64 v161, v52, -s12
	v_mul_f32_e32 v160, v160, v155
	v_mul_f32_e32 v161, v161, v155
	v_add_u32_e32 v162, 0x800, v137
	ds_write2_b32 v162, v161, v160 offset0:128 offset1:160
	v_mul_f32_e64 v160, v20, -s12
	v_mul_f32_e64 v161, v4, -s12
	v_mul_f32_e32 v160, v160, v155
	v_mul_f32_e32 v161, v161, v155
	v_add_u32_e32 v162, 0x800, v136
	ds_write2_b32 v162, v161, v160 offset0:192 offset1:224
	v_mul_f32_e64 v160, v101, -s12
	v_mul_f32_e64 v161, v117, -s12
	v_mul_f32_e32 v160, v160, v153
	v_mul_f32_e32 v161, v161, v153
	v_add_u32_e32 v162, 0xc00, v135
	ds_write2_b32 v162, v161, v160 offset1:32
	v_mul_f32_e64 v160, v69, -s12
	v_mul_f32_e64 v161, v85, -s12
	v_mul_f32_e32 v160, v160, v153
	v_mul_f32_e32 v161, v161, v153
	v_add_u32_e32 v162, 0xc00, v133
	ds_write2_b32 v162, v161, v160 offset0:64 offset1:96
	v_mul_f32_e64 v160, v37, -s12
	v_mul_f32_e64 v161, v53, -s12
	v_mul_f32_e32 v160, v160, v153
	v_mul_f32_e32 v161, v161, v153
	v_add_u32_e32 v162, 0xc00, v132
	ds_write2_b32 v162, v161, v160 offset0:128 offset1:160
	v_mul_f32_e64 v160, v21, -s12
	v_mul_f32_e64 v161, v5, -s12
	v_mul_f32_e32 v160, v160, v153
	v_mul_f32_e32 v161, v161, v153
	v_add_u32_e32 v162, 0xc00, v131
	ds_write2_b32 v162, v161, v160 offset0:192 offset1:224
	v_mul_f32_e64 v160, v102, -s12
	v_mul_f32_e64 v161, v118, -s12
	v_mul_f32_e32 v160, v160, v152
	v_mul_f32_e32 v161, v161, v152
	ds_write2_b32 v154, v160, v161 offset1:32
	v_mul_f32_e64 v160, v70, -s12
	v_mul_f32_e64 v161, v86, -s12
	v_mul_f32_e32 v160, v160, v152
	v_mul_f32_e32 v161, v161, v152
	v_add_u32_e32 v162, 0x2000, v138
	ds_write2_b32 v162, v160, v161 offset0:64 offset1:96
	v_mul_f32_e64 v160, v38, -s12
	v_mul_f32_e64 v161, v54, -s12
	v_mul_f32_e32 v160, v160, v152
	v_mul_f32_e32 v161, v161, v152
	v_add_u32_e32 v162, 0x2000, v137
	ds_write2_b32 v162, v160, v161 offset0:128 offset1:160
	v_mul_f32_e64 v160, v22, -s12
	v_mul_f32_e64 v161, v6, -s12
	v_mul_f32_e32 v160, v160, v152
	v_mul_f32_e32 v161, v161, v152
	v_add_u32_e32 v162, 0x2000, v136
	ds_write2_b32 v162, v160, v161 offset0:192 offset1:224
	v_mul_f32_e64 v160, v103, -s12
	v_mul_f32_e64 v161, v119, -s12
	v_mul_f32_e32 v160, v160, v150
	v_mul_f32_e32 v161, v161, v150
	v_add_u32_e32 v162, 0x2400, v135
	ds_write2_b32 v162, v160, v161 offset1:32
	v_mul_f32_e64 v160, v71, -s12
	v_mul_f32_e64 v161, v87, -s12
	v_mul_f32_e32 v160, v160, v150
	v_mul_f32_e32 v161, v161, v150
	v_add_u32_e32 v162, 0x2400, v133
	ds_write2_b32 v162, v160, v161 offset0:64 offset1:96
	v_mul_f32_e64 v160, v39, -s12
	v_mul_f32_e64 v161, v55, -s12
	v_mul_f32_e32 v160, v160, v150
	v_mul_f32_e32 v161, v161, v150
	v_add_u32_e32 v162, 0x2400, v132
	ds_write2_b32 v162, v160, v161 offset0:128 offset1:160
	v_mul_f32_e64 v160, v23, -s12
	v_mul_f32_e64 v161, v7, -s12
	v_mul_f32_e32 v160, v160, v150
	v_mul_f32_e32 v161, v161, v150
	v_add_u32_e32 v162, 0x2400, v131
; __device__ __forceinline__ void attn_unit(const bf16* __restrict__ qkvb, int seq, int q0, int h, ldsp_t ldsb, float* wsc, const float* tab, float lam) {
;     ...
;   if (mapw) {
; #pragma unroll
;     for (int r = 0; r < 16; ++r)
; #pragma unroll
;       for (int d = 0; d < 8; ++d) df[((r & 3) + 8 * (r >> 2)) * 256 + ((d * 32 + r32) ^ ((d >> 1) << 2) ^ ((r & 3) << 4))] = -lam * o[d][r] * rli[r];
;   }
	ds_write2_b32 v162, v160, v161 offset0:192 offset1:224
	v_mul_f32_e64 v160, v104, -s12
	v_mul_f32_e64 v161, v120, -s12
	v_mul_f32_e32 v160, v160, v149
	v_mul_f32_e32 v161, v161, v149
	ds_write2_b32 v151, v161, v160 offset1:32
	v_mul_f32_e64 v160, v72, -s12
	v_mul_f32_e64 v161, v88, -s12
	v_mul_f32_e32 v160, v160, v149
	v_mul_f32_e32 v161, v161, v149
	v_add_u32_e32 v162, 0x2800, v138
	ds_write2_b32 v162, v161, v160 offset0:64 offset1:96
	v_mul_f32_e64 v160, v40, -s12
	v_mul_f32_e64 v161, v56, -s12
	v_mul_f32_e32 v160, v160, v149
	v_mul_f32_e32 v161, v161, v149
	v_add_u32_e32 v162, 0x2800, v137
	ds_write2_b32 v162, v161, v160 offset0:128 offset1:160
	v_mul_f32_e64 v160, v24, -s12
	v_mul_f32_e64 v161, v8, -s12
	v_mul_f32_e32 v160, v160, v149
	v_mul_f32_e32 v161, v161, v149
	v_add_u32_e32 v162, 0x2800, v136
	ds_write2_b32 v162, v161, v160 offset0:192 offset1:224
	v_mul_f32_e64 v160, v105, -s12
	v_mul_f32_e64 v161, v121, -s12
	v_mul_f32_e32 v160, v160, v147
	v_mul_f32_e32 v161, v161, v147
	v_add_u32_e32 v162, 0x2c00, v135
	ds_write2_b32 v162, v161, v160 offset1:32
	v_mul_f32_e64 v160, v73, -s12
	v_mul_f32_e64 v161, v89, -s12
	v_mul_f32_e32 v160, v160, v147
	v_mul_f32_e32 v161, v161, v147
	v_add_u32_e32 v162, 0x2c00, v133
	ds_write2_b32 v162, v161, v160 offset0:64 offset1:96
	v_mul_f32_e64 v160, v41, -s12
	v_mul_f32_e64 v161, v57, -s12
	v_mul_f32_e32 v160, v160, v147
	v_mul_f32_e32 v161, v161, v147
	v_add_u32_e32 v162, 0x2c00, v132
	ds_write2_b32 v162, v161, v160 offset0:128 offset1:160
	v_mul_f32_e64 v160, v25, -s12
	v_mul_f32_e64 v161, v9, -s12
	v_mul_f32_e32 v160, v160, v147
	v_mul_f32_e32 v161, v161, v147
	v_add_u32_e32 v162, 0x2c00, v131
	ds_write2_b32 v162, v161, v160 offset0:192 offset1:224
	v_mul_f32_e64 v160, v106, -s12
	v_mul_f32_e64 v161, v122, -s12
	v_mul_f32_e32 v160, v160, v146
	v_mul_f32_e32 v161, v161, v146
	ds_write2_b32 v148, v160, v161 offset1:32
	v_mul_f32_e64 v160, v74, -s12
	v_mul_f32_e64 v161, v90, -s12
	v_mul_f32_e32 v160, v160, v146
	v_mul_f32_e32 v161, v161, v146
	v_add_u32_e32 v162, 0x4000, v138
	ds_write2_b32 v162, v160, v161 offset0:64 offset1:96
	v_mul_f32_e64 v160, v42, -s12
	v_mul_f32_e64 v161, v58, -s12
	v_mul_f32_e32 v160, v160, v146
	v_mul_f32_e32 v161, v161, v146
	v_add_u32_e32 v162, 0x4000, v137
	ds_write2_b32 v162, v160, v161 offset0:128 offset1:160
	v_mul_f32_e64 v160, v26, -s12
	v_mul_f32_e64 v161, v10, -s12
	v_mul_f32_e32 v160, v160, v146
	v_mul_f32_e32 v161, v161, v146
	v_add_u32_e32 v162, 0x4000, v136
	ds_write2_b32 v162, v160, v161 offset0:192 offset1:224
	v_mul_f32_e64 v160, v107, -s12
	v_mul_f32_e64 v161, v123, -s12
	v_mul_f32_e32 v160, v160, v144
	v_mul_f32_e32 v161, v161, v144
	v_add_u32_e32 v162, 0x4400, v135
	ds_write2_b32 v162, v160, v161 offset1:32
	v_mul_f32_e64 v160, v75, -s12
	v_mul_f32_e64 v161, v91, -s12
	v_mul_f32_e32 v160, v160, v144
	v_mul_f32_e32 v161, v161, v144
	v_add_u32_e32 v162, 0x4400, v133
	ds_write2_b32 v162, v160, v161 offset0:64 offset1:96
	v_mul_f32_e64 v160, v43, -s12
	v_mul_f32_e64 v161, v59, -s12
	v_mul_f32_e32 v160, v160, v144
	v_mul_f32_e32 v161, v161, v144
	v_add_u32_e32 v162, 0x4400, v132
	ds_write2_b32 v162, v160, v161 offset0:128 offset1:160
	v_mul_f32_e64 v160, v27, -s12
	v_mul_f32_e64 v161, v11, -s12
	v_mul_f32_e32 v160, v160, v144
	v_mul_f32_e32 v161, v161, v144
	v_add_u32_e32 v162, 0x4400, v131
	ds_write2_b32 v162, v160, v161 offset0:192 offset1:224
	v_mul_f32_e64 v160, v108, -s12
	v_mul_f32_e64 v161, v124, -s12
	v_mul_f32_e32 v160, v160, v143
	v_mul_f32_e32 v161, v161, v143
	ds_write2_b32 v145, v161, v160 offset1:32
	v_mul_f32_e64 v160, v76, -s12
	v_mul_f32_e64 v161, v92, -s12
	v_mul_f32_e32 v160, v160, v143
	v_mul_f32_e32 v161, v161, v143
	v_add_u32_e32 v162, 0x4800, v138
	ds_write2_b32 v162, v161, v160 offset0:64 offset1:96
	v_mul_f32_e64 v160, v44, -s12
	v_mul_f32_e64 v161, v60, -s12
	v_mul_f32_e32 v160, v160, v143
	v_mul_f32_e32 v161, v161, v143
	v_add_u32_e32 v162, 0x4800, v137
	ds_write2_b32 v162, v161, v160 offset0:128 offset1:160
	v_mul_f32_e64 v160, v28, -s12
	v_mul_f32_e64 v161, v12, -s12
	v_mul_f32_e32 v160, v160, v143
	v_mul_f32_e32 v161, v161, v143
	v_add_u32_e32 v162, 0x4800, v136
	ds_write2_b32 v162, v161, v160 offset0:192 offset1:224
; __device__ __forceinline__ void attn_unit(const bf16* __restrict__ qkvb, int seq, int q0, int h, ldsp_t ldsb, float* wsc, const float* tab, float lam) {
;     ...
;   if (mapw) {
; #pragma unroll
;     for (int r = 0; r < 16; ++r)
; #pragma unroll
;       for (int d = 0; d < 8; ++d) df[((r & 3) + 8 * (r >> 2)) * 256 + ((d * 32 + r32) ^ ((d >> 1) << 2) ^ ((r & 3) << 4))] = -lam * o[d][r] * rli[r];
;   }
	v_mul_f32_e64 v160, v109, -s12
	v_mul_f32_e64 v161, v125, -s12
	v_mul_f32_e32 v160, v160, v142
	v_mul_f32_e32 v161, v161, v142
	v_add_u32_e32 v162, 0x4c00, v135
	ds_write2_b32 v162, v161, v160 offset1:32
	v_mul_f32_e64 v160, v77, -s12
	v_mul_f32_e64 v161, v93, -s12
	v_mul_f32_e32 v160, v160, v142
	v_mul_f32_e32 v161, v161, v142
	v_add_u32_e32 v162, 0x4c00, v133
	ds_write2_b32 v162, v161, v160 offset0:64 offset1:96
	v_mul_f32_e64 v160, v45, -s12
	v_mul_f32_e64 v161, v61, -s12
	v_mul_f32_e32 v160, v160, v142
	v_mul_f32_e32 v161, v161, v142
	v_add_u32_e32 v162, 0x4c00, v132
	ds_write2_b32 v162, v161, v160 offset0:128 offset1:160
	v_mul_f32_e64 v160, v29, -s12
	v_mul_f32_e64 v161, v13, -s12
	v_mul_f32_e32 v160, v160, v142
	v_mul_f32_e32 v161, v161, v142
	v_add_u32_e32 v162, 0x4c00, v131
	ds_write2_b32 v162, v161, v160 offset0:192 offset1:224
	v_mul_f32_e64 v160, v110, -s12
	v_mul_f32_e64 v161, v126, -s12
	v_mul_f32_e32 v160, v160, v141
	v_mul_f32_e32 v161, v161, v141
	ds_write2_b32 v1, v160, v161 offset1:32
	v_mul_f32_e64 v160, v78, -s12
	v_mul_f32_e64 v161, v94, -s12
	v_mul_f32_e32 v160, v160, v141
	v_mul_f32_e32 v161, v161, v141
	v_add_u32_e32 v162, 0x6000, v138
	ds_write2_b32 v162, v160, v161 offset0:64 offset1:96
	v_mul_f32_e64 v160, v46, -s12
	v_mul_f32_e64 v161, v62, -s12
	v_mul_f32_e32 v160, v160, v141
	v_mul_f32_e32 v161, v161, v141
	v_add_u32_e32 v162, 0x6000, v137
	ds_write2_b32 v162, v160, v161 offset0:128 offset1:160
	v_mul_f32_e64 v160, v30, -s12
	v_mul_f32_e64 v161, v14, -s12
	v_mul_f32_e32 v160, v160, v141
	v_mul_f32_e32 v161, v161, v141
	v_add_u32_e32 v162, 0x6000, v136
	ds_write2_b32 v162, v160, v161 offset0:192 offset1:224
	v_mul_f32_e64 v160, v111, -s12
	v_mul_f32_e64 v161, v127, -s12
	v_mul_f32_e32 v160, v160, v139
	v_mul_f32_e32 v161, v161, v139
	v_add_u32_e32 v162, 0x6400, v135
	ds_write2_b32 v162, v160, v161 offset1:32
	v_mul_f32_e64 v160, v79, -s12
	v_mul_f32_e64 v161, v95, -s12
	v_mul_f32_e32 v160, v160, v139
	v_mul_f32_e32 v161, v161, v139
	v_add_u32_e32 v162, 0x6400, v133
	ds_write2_b32 v162, v160, v161 offset0:64 offset1:96
	v_mul_f32_e64 v160, v47, -s12
	v_mul_f32_e64 v161, v63, -s12
	v_mul_f32_e32 v160, v160, v139
	v_mul_f32_e32 v161, v161, v139
	v_add_u32_e32 v162, 0x6400, v132
	ds_write2_b32 v162, v160, v161 offset0:128 offset1:160
	v_mul_f32_e64 v160, v31, -s12
	v_mul_f32_e64 v161, v15, -s12
	v_mul_f32_e32 v160, v160, v139
	v_mul_f32_e32 v161, v161, v139
	v_add_u32_e32 v162, 0x6400, v131
	ds_write2_b32 v162, v160, v161 offset0:192 offset1:224
	v_mul_f32_e64 v160, v112, -s12
	v_mul_f32_e64 v161, v128, -s12
	v_mul_f32_e32 v160, v160, v134
	v_mul_f32_e32 v161, v161, v134
	ds_write2_b32 v140, v161, v160 offset1:32
	v_mul_f32_e64 v160, v80, -s12
	v_mul_f32_e64 v161, v96, -s12
	v_mul_f32_e32 v160, v160, v134
	v_mul_f32_e32 v161, v161, v134
	v_add_u32_e32 v162, 0x6800, v138
	ds_write2_b32 v162, v161, v160 offset0:64 offset1:96
	v_mul_f32_e64 v160, v48, -s12
	v_mul_f32_e64 v161, v64, -s12
	v_mul_f32_e32 v160, v160, v134
	v_mul_f32_e32 v161, v161, v134
	v_add_u32_e32 v162, 0x6800, v137
	ds_write2_b32 v162, v161, v160 offset0:128 offset1:160
	v_mul_f32_e64 v160, v32, -s12
	v_mul_f32_e64 v161, v16, -s12
	v_mul_f32_e32 v160, v160, v134
	v_mul_f32_e32 v161, v161, v134
	v_add_u32_e32 v162, 0x6800, v136
	ds_write2_b32 v162, v161, v160 offset0:192 offset1:224
	v_mul_f32_e64 v160, v113, -s12
	v_mul_f32_e64 v161, v129, -s12
	v_mul_f32_e32 v160, v160, v130
	v_mul_f32_e32 v161, v161, v130
	v_add_u32_e32 v162, 0x6c00, v135
	ds_write2_b32 v162, v161, v160 offset1:32
	v_mul_f32_e64 v160, v81, -s12
	v_mul_f32_e64 v161, v97, -s12
	v_mul_f32_e32 v160, v160, v130
	v_mul_f32_e32 v161, v161, v130
	v_add_u32_e32 v162, 0x6c00, v133
	ds_write2_b32 v162, v161, v160 offset0:64 offset1:96
	v_mul_f32_e64 v160, v49, -s12
	v_mul_f32_e64 v161, v65, -s12
	v_mul_f32_e32 v160, v160, v130
	v_mul_f32_e32 v161, v161, v130
	v_add_u32_e32 v162, 0x6c00, v132
	ds_write2_b32 v162, v161, v160 offset0:128 offset1:160
	v_mul_f32_e64 v160, v33, -s12
	v_mul_f32_e64 v161, v17, -s12
	v_mul_f32_e32 v160, v160, v130
	v_mul_f32_e32 v161, v161, v130
	v_add_u32_e32 v162, 0x6c00, v131
	ds_write2_b32 v162, v161, v160 offset0:192 offset1:224

; #define GAS __attribute__((address_space(1)))
; __device__ __forceinline__ void ln_rows_b(const Frame& F, const bf16* src, float* dstf, bf16* dstb, float* must, const float* gam, const float* bet, int nrows, bool poison) {
;     ...
;         float v[4][8]; float s = 0.f;
; #pragma unroll
;         for (int j = 0; j < 4; ++j) { const v4u w = wc[j];
;             v[j][0] = __uint_as_float(w.x << 16); v[j][1] = __uint_as_float(w.x & 0xffff0000u); v[j][2] = __uint_as_float(w.y << 16); v[j][3] = __uint_as_float(w.y & 0xffff0000u);
;             v[j][4] = __uint_as_float(w.z << 16); v[j][5] = __uint_as_float(w.z & 0xffff0000u); v[j][6] = __uint_as_float(w.w << 16); v[j][7] = __uint_as_float(w.w & 0xffff0000u);
; #pragma unroll
;             for (int e = 0; e < 8; ++e) s += v[j][e]; }
;         const float mean = wave_sum(s, F.lane) * (1.f / DM); float s2 = 0.f;
; #pragma unroll
;         for (int j = 0; j < 4; ++j)
; #pragma unroll
;             for (int e = 0; e < 8; ++e) { v[j][e] -= mean; s2 += v[j][e] * v[j][e]; }
;         const float rstd = 1.f / sqrtf(wave_sum(s2, F.lane) * (1.f / DM) + LN_EPS);
;         if (must && F.lane == 0) { float2 o2; o2.x = mean; o2.y = rstd; *(float2*)(must + (size_t)m * 2) = o2; }
; #pragma unroll
;         for (int j = 0; j < 4; ++j) { const int c0 = (64 * j + F.lane) * 8;
;             const f32x4 g0 = *(const GAS f32x4*)(gam + c0), g1 = *(const GAS f32x4*)(gam + c0 + 4), b0 = *(const GAS f32x4*)(bet + c0), b1 = *(const GAS f32x4*)(bet + c0 + 4);
.LBB0_1073:
	v_lshlrev_b32_e32 v52, 16, v28
	v_and_b32_e32 v53, 0xffff0000, v28
	v_add_f32_e32 v69, 0, v52
	v_lshlrev_b32_e32 v28, 16, v29
	v_add_f32_e32 v69, v69, v53
	v_and_b32_e32 v29, 0xffff0000, v29
	v_add_f32_e32 v69, v69, v28
	v_lshlrev_b32_e32 v54, 16, v30
	v_add_f32_e32 v69, v69, v29
	v_and_b32_e32 v55, 0xffff0000, v30
	v_add_f32_e32 v69, v69, v54
	v_lshlrev_b32_e32 v30, 16, v31
	v_add_f32_e32 v69, v69, v55
	v_and_b32_e32 v31, 0xffff0000, v31
	v_add_f32_e32 v69, v69, v30
	v_lshlrev_b32_e32 v56, 16, v24
	v_add_f32_e32 v69, v69, v31
	v_and_b32_e32 v57, 0xffff0000, v24
	v_add_f32_e32 v69, v69, v56
	v_lshlrev_b32_e32 v24, 16, v25
	v_add_f32_e32 v69, v69, v57
	v_and_b32_e32 v25, 0xffff0000, v25
	v_add_f32_e32 v69, v69, v24
	v_lshlrev_b32_e32 v58, 16, v26
	v_add_f32_e32 v69, v69, v25
	v_and_b32_e32 v59, 0xffff0000, v26
	v_add_f32_e32 v69, v69, v58
	v_lshlrev_b32_e32 v26, 16, v27
	v_add_f32_e32 v69, v69, v59
	v_and_b32_e32 v27, 0xffff0000, v27
	v_add_f32_e32 v69, v69, v26
	v_lshlrev_b32_e32 v70, 16, v20
	v_add_f32_e32 v69, v69, v27
	v_and_b32_e32 v71, 0xffff0000, v20
	v_add_f32_e32 v69, v69, v70
	v_lshlrev_b32_e32 v20, 16, v21
	v_add_f32_e32 v69, v69, v71
	v_and_b32_e32 v21, 0xffff0000, v21
	v_add_f32_e32 v69, v69, v20
	v_lshlrev_b32_e32 v72, 16, v22
	v_add_f32_e32 v69, v69, v21
	v_and_b32_e32 v73, 0xffff0000, v22
	v_add_f32_e32 v69, v69, v72
	v_lshlrev_b32_e32 v22, 16, v23
	v_add_f32_e32 v69, v69, v73
	v_and_b32_e32 v23, 0xffff0000, v23
	v_add_f32_e32 v69, v69, v22
	v_lshlrev_b32_e32 v74, 16, v16
	v_add_f32_e32 v69, v69, v23
	v_and_b32_e32 v75, 0xffff0000, v16
	v_add_f32_e32 v69, v69, v74
	v_lshlrev_b32_e32 v16, 16, v17
	v_add_f32_e32 v69, v69, v75
	v_and_b32_e32 v17, 0xffff0000, v17
	v_add_f32_e32 v69, v69, v16
	v_lshlrev_b32_e32 v76, 16, v18
	v_add_f32_e32 v69, v69, v17
	v_and_b32_e32 v77, 0xffff0000, v18
	v_add_f32_e32 v69, v69, v76
	v_and_b32_e32 v18, 0xffff0000, v19
	v_lshlrev_b32_e32 v19, 16, v19
	v_add_f32_e32 v69, v69, v77
	v_add_f32_e32 v69, v69, v19
	v_add_f32_e32 v69, v69, v18
	ds_bpermute_b32 v78, v60, v69
	v_lshl_add_u64 v[50:51], v[50:51], 0, s[10:11]
	s_waitcnt lgkmcnt(0)
	v_add_f32_e32 v69, v69, v78
	ds_bpermute_b32 v78, v61, v69
	s_waitcnt lgkmcnt(0)
	v_add_f32_e32 v69, v69, v78
	ds_bpermute_b32 v78, v62, v69
	s_waitcnt lgkmcnt(0)
	v_add_f32_e32 v69, v69, v78
	ds_bpermute_b32 v78, v63, v69
	s_waitcnt lgkmcnt(0)
	v_add_f32_e32 v69, v69, v78
	ds_bpermute_b32 v78, v64, v69
	s_waitcnt lgkmcnt(0)
	v_add_f32_e32 v69, v69, v78
	ds_bpermute_b32 v78, v65, v69
	s_waitcnt lgkmcnt(0)
	v_add_f32_e32 v69, v69, v78
	v_mul_f32_e32 v78, 0x3a000000, v69
	v_pk_add_f32 v[80:81], v[52:53], v[78:79] op_sel_hi:[1,0] neg_lo:[0,1] neg_hi:[0,1]
	v_pk_add_f32 v[84:85], v[28:29], v[78:79] op_sel_hi:[1,0] neg_lo:[0,1] neg_hi:[0,1]
	v_pk_mul_f32 v[82:83], v[80:81], v[80:81]
	v_pk_mul_f32 v[28:29], v[84:85], v[84:85]
	v_pk_add_f32 v[98:99], v[58:59], v[78:79] op_sel_hi:[1,0] neg_lo:[0,1] neg_hi:[0,1]
	v_pk_add_f32 v[58:59], v[18:19], v[78:79] op_sel_hi:[1,0] neg_lo:[0,1] neg_hi:[0,1]
	v_add_f32_e32 v18, v82, v83
	v_pk_add_f32 v[86:87], v[54:55], v[78:79] op_sel_hi:[1,0] neg_lo:[0,1] neg_hi:[0,1]
	v_add_f32_e32 v18, v28, v18
	v_pk_mul_f32 v[88:89], v[86:87], v[86:87]
	v_add_f32_e32 v18, v29, v18
	v_pk_add_f32 v[90:91], v[30:31], v[78:79] op_sel_hi:[1,0] neg_lo:[0,1] neg_hi:[0,1]
	v_add_f32_e32 v18, v88, v18
	v_pk_mul_f32 v[30:31], v[90:91], v[90:91]
	v_add_f32_e32 v18, v89, v18
	v_pk_add_f32 v[92:93], v[56:57], v[78:79] op_sel_hi:[1,0] neg_lo:[0,1] neg_hi:[0,1]
	v_add_f32_e32 v18, v30, v18
	v_pk_mul_f32 v[94:95], v[92:93], v[92:93]
	v_add_f32_e32 v18, v31, v18
	v_pk_add_f32 v[96:97], v[24:25], v[78:79] op_sel_hi:[1,0] neg_lo:[0,1] neg_hi:[0,1]
	v_add_f32_e32 v18, v94, v18
	v_pk_mul_f32 v[24:25], v[96:97], v[96:97]
	v_add_f32_e32 v18, v95, v18
	v_add_f32_e32 v18, v24, v18
	v_pk_mul_f32 v[100:101], v[98:99], v[98:99]
	v_add_f32_e32 v18, v25, v18
	v_pk_add_f32 v[102:103], v[26:27], v[78:79] op_sel_hi:[1,0] neg_lo:[0,1] neg_hi:[0,1]
	v_add_f32_e32 v18, v100, v18
	v_pk_mul_f32 v[26:27], v[102:103], v[102:103]
	v_add_f32_e32 v18, v101, v18
	v_pk_add_f32 v[70:71], v[70:71], v[78:79] op_sel_hi:[1,0] neg_lo:[0,1] neg_hi:[0,1]
	v_add_f32_e32 v18, v26, v18
	v_pk_mul_f32 v[104:105], v[70:71], v[70:71]
	v_add_f32_e32 v18, v27, v18
	v_pk_add_f32 v[106:107], v[20:21], v[78:79] op_sel_hi:[1,0] neg_lo:[0,1] neg_hi:[0,1]
	v_add_f32_e32 v18, v104, v18
	v_pk_mul_f32 v[20:21], v[106:107], v[106:107]
	v_add_f32_e32 v18, v105, v18
	v_pk_add_f32 v[72:73], v[72:73], v[78:79] op_sel_hi:[1,0] neg_lo:[0,1] neg_hi:[0,1]
	v_add_f32_e32 v18, v20, v18
	v_pk_mul_f32 v[108:109], v[72:73], v[72:73]
	v_add_f32_e32 v18, v21, v18
	v_pk_add_f32 v[110:111], v[22:23], v[78:79] op_sel_hi:[1,0] neg_lo:[0,1] neg_hi:[0,1]
	v_add_f32_e32 v18, v108, v18
	v_pk_mul_f32 v[22:23], v[110:111], v[110:111]
	v_add_f32_e32 v18, v109, v18
	v_pk_add_f32 v[52:53], v[74:75], v[78:79] op_sel_hi:[1,0] neg_lo:[0,1] neg_hi:[0,1]
	v_add_f32_e32 v18, v22, v18
	v_pk_mul_f32 v[74:75], v[52:53], v[52:53]
	v_add_f32_e32 v18, v23, v18
	v_pk_add_f32 v[54:55], v[16:17], v[78:79] op_sel_hi:[1,0] neg_lo:[0,1] neg_hi:[0,1]
	v_add_f32_e32 v18, v74, v18
	v_pk_mul_f32 v[16:17], v[54:55], v[54:55]
	v_add_f32_e32 v18, v75, v18
	v_add_f32_e32 v16, v16, v18
	v_add_f32_e32 v69, v17, v16
	global_load_dwordx4 v[16:19], v[32:33], off offset:16
	global_load_dwordx4 v[20:23], v[32:33], off
	global_load_dwordx4 v[24:27], v[34:35], off offset:16
	global_load_dwordx4 v[28:31], v[34:35], off
	v_pk_add_f32 v[56:57], v[76:77], v[78:79] op_sel_hi:[1,0] neg_lo:[0,1] neg_hi:[0,1]
	v_pk_mul_f32 v[78:79], v[58:59], v[58:59]
	v_pk_mul_f32 v[76:77], v[56:57], v[56:57]
	s_nop 0
	v_add_f32_e32 v69, v76, v69
	v_add_f32_e32 v69, v77, v69
	v_add_f32_e32 v69, v79, v69
	v_add_f32_e32 v69, v78, v69
	ds_bpermute_b32 v74, v60, v69
	s_waitcnt lgkmcnt(0)
; #define GAS __attribute__((address_space(1)))
; __device__ __forceinline__ unsigned pk2(float lo, float hi) { return f2bf(lo) | (f2bf(hi) << 16); }
; __device__ __forceinline__ void ln_rows_b(const Frame& F, const bf16* src, float* dstf, bf16* dstb, float* must, const float* gam, const float* bet, int nrows, bool poison) {
;     ...
;         const float rstd = 1.f / sqrtf(wave_sum(s2, F.lane) * (1.f / DM) + LN_EPS);
;         if (must && F.lane == 0) { float2 o2; o2.x = mean; o2.y = rstd; *(float2*)(must + (size_t)m * 2) = o2; }
; #pragma unroll
;         for (int j = 0; j < 4; ++j) { const int c0 = (64 * j + F.lane) * 8;
;             const f32x4 g0 = *(const GAS f32x4*)(gam + c0), g1 = *(const GAS f32x4*)(gam + c0 + 4), b0 = *(const GAS f32x4*)(bet + c0), b1 = *(const GAS f32x4*)(bet + c0 + 4);
;             f32x4 o0 = (f32x4){v[j][0], v[j][1], v[j][2], v[j][3]} * rstd * g0 + b0, o1 = (f32x4){v[j][4], v[j][5], v[j][6], v[j][7]} * rstd * g1 + b1;
;             if (poison) { const float q = __builtin_nanf(""); o0 = (f32x4){q, q, q, q}; o1 = o0; }
;             if (dstf) { *(GAS f32x4*)(dstf + (size_t)m * DM + c0) = o0; *(GAS f32x4*)(dstf + (size_t)m * DM + c0 + 4) = o1; }
;             if (dstb) { v4u w; w.x = pk2(o0.x, o0.y); w.y = pk2(o0.z, o0.w); w.z = pk2(o1.x, o1.y); w.w = pk2(o1.z, o1.w); *(GAS v4u*)(dstb + (size_t)m * DM + c0) = w; } }
	v_add_f32_e32 v69, v69, v74
	ds_bpermute_b32 v74, v61, v69
	s_waitcnt lgkmcnt(0)
	v_add_f32_e32 v69, v69, v74
	ds_bpermute_b32 v74, v62, v69
	s_waitcnt lgkmcnt(0)
	v_add_f32_e32 v69, v69, v74
	ds_bpermute_b32 v74, v63, v69
	s_waitcnt lgkmcnt(0)
	v_add_f32_e32 v69, v69, v74
	ds_bpermute_b32 v74, v64, v69
	s_waitcnt lgkmcnt(0)
	v_add_f32_e32 v69, v69, v74
	ds_bpermute_b32 v74, v65, v69
	s_waitcnt lgkmcnt(0)
	v_add_f32_e32 v69, v69, v74
	v_fmamk_f32 v69, v69, 0x3a000000, v66
	v_mul_f32_e32 v74, 0x4f800000, v69
	v_cmp_gt_f32_e32 vcc, s5, v69
	s_nop 1
	v_cndmask_b32_e32 v69, v69, v74, vcc
	v_sqrt_f32_e32 v74, v69
	s_nop 0
	v_add_u32_e32 v75, -1, v74
	v_fma_f32 v76, -v75, v74, v69
	v_cmp_ge_f32_e64 s[2:3], 0, v76
	v_add_u32_e32 v76, 1, v74
	s_nop 0
	v_cndmask_b32_e64 v75, v74, v75, s[2:3]
	v_fma_f32 v74, -v76, v74, v69
	v_cmp_lt_f32_e64 s[2:3], 0, v74
	s_nop 1
	v_cndmask_b32_e64 v74, v75, v76, s[2:3]
	v_mul_f32_e32 v75, 0x37800000, v74
	v_cndmask_b32_e32 v74, v74, v75, vcc
	v_cmp_class_f32_e32 vcc, v69, v67
	s_nop 1
	v_cndmask_b32_e32 v69, v74, v69, vcc
	v_div_scale_f32 v74, s[2:3], v69, v69, 1.0
	v_rcp_f32_e32 v75, v74
	s_nop 0
	v_fma_f32 v76, -v74, v75, 1.0
	v_fmac_f32_e32 v75, v76, v75
	v_div_scale_f32 v76, vcc, 1.0, v69, 1.0
	v_mul_f32_e32 v77, v76, v75
	v_fma_f32 v78, -v74, v77, v76
	v_fmac_f32_e32 v77, v78, v75
	v_fma_f32 v74, -v74, v77, v76
	v_div_fmas_f32 v74, v74, v75, v77
	v_div_fixup_f32 v88, v74, v69, 1.0
	v_pk_mul_f32 v[74:75], v[84:85], v[88:89] op_sel_hi:[1,0]
	v_pk_mul_f32 v[76:77], v[80:81], v[88:89] op_sel_hi:[1,0]
	s_waitcnt vmcnt(0)
	v_pk_fma_f32 v[22:23], v[22:23], v[74:75], v[30:31]
	v_pk_fma_f32 v[20:21], v[20:21], v[76:77], v[28:29]
	v_pk_mul_f32 v[28:29], v[90:91], v[88:89] op_sel_hi:[1,0]
	v_pk_mul_f32 v[30:31], v[86:87], v[88:89] op_sel_hi:[1,0]
	v_pk_fma_f32 v[26:27], v[18:19], v[28:29], v[26:27]
	v_pk_fma_f32 v[24:25], v[16:17], v[30:31], v[24:25]
	v_cndmask_b32_e64 v19, v68, v23, s[0:1]
	v_cndmask_b32_e64 v18, v68, v22, s[0:1]
	v_cndmask_b32_e64 v17, v68, v21, s[0:1]
	v_cndmask_b32_e64 v16, v68, v20, s[0:1]
	v_cndmask_b32_e64 v23, v68, v27, s[0:1]
	v_cndmask_b32_e64 v22, v68, v26, s[0:1]
	v_cndmask_b32_e64 v21, v68, v25, s[0:1]
	v_cndmask_b32_e64 v20, v68, v24, s[0:1]
	global_store_dwordx4 v[48:49], v[16:19], off nt
	global_store_dwordx4 v[48:49], v[20:23], off offset:16 nt
	global_load_dwordx4 v[16:19], v[38:39], off
	s_nop 0
	global_load_dwordx4 v[20:23], v[36:37], off
	global_load_dwordx4 v[24:27], v[36:37], off offset:16
	global_load_dwordx4 v[28:31], v[38:39], off offset:16
	v_pk_mul_f32 v[74:75], v[92:93], v[88:89] op_sel_hi:[1,0]
	v_pk_mul_f32 v[76:77], v[96:97], v[88:89] op_sel_hi:[1,0]
	v_pk_mul_f32 v[78:79], v[98:99], v[88:89] op_sel_hi:[1,0]
	v_pk_mul_f32 v[80:81], v[102:103], v[88:89] op_sel_hi:[1,0]
	v_pk_mul_f32 v[70:71], v[70:71], v[88:89] op_sel_hi:[1,0]
	v_add_co_u32_e32 v86, vcc, s14, v48
	v_pk_mul_f32 v[72:73], v[72:73], v[88:89] op_sel_hi:[1,0]
	s_nop 0
	v_addc_co_u32_e32 v87, vcc, 0, v49, vcc
	s_andn2_b64 vcc, exec, s[12:13]
	s_waitcnt vmcnt(2)
	v_pk_fma_f32 v[18:19], v[22:23], v[76:77], v[18:19]
	v_pk_fma_f32 v[16:17], v[20:21], v[74:75], v[16:17]
	s_waitcnt vmcnt(0)
	v_pk_fma_f32 v[22:23], v[26:27], v[80:81], v[30:31]
	v_pk_fma_f32 v[20:21], v[24:25], v[78:79], v[28:29]
	v_cndmask_b32_e64 v17, v68, v17, s[0:1]
	v_cndmask_b32_e64 v16, v68, v16, s[0:1]
	v_cndmask_b32_e64 v19, v68, v19, s[0:1]
	v_cndmask_b32_e64 v18, v68, v18, s[0:1]
	v_cndmask_b32_e64 v21, v68, v21, s[0:1]
	v_cndmask_b32_e64 v20, v68, v20, s[0:1]
	v_cndmask_b32_e64 v23, v68, v23, s[0:1]
	v_cndmask_b32_e64 v22, v68, v22, s[0:1]
	global_store_dwordx4 v[48:49], v[16:19], off offset:2048 nt
	global_store_dwordx4 v[48:49], v[20:23], off offset:2064 nt
	global_load_dwordx4 v[16:19], v[42:43], off
	s_nop 0
	global_load_dwordx4 v[20:23], v[40:41], off
	global_load_dwordx4 v[24:27], v[40:41], off offset:16
	global_load_dwordx4 v[28:31], v[42:43], off offset:16
	v_pk_mul_f32 v[74:75], v[106:107], v[88:89] op_sel_hi:[1,0]
	v_pk_mul_f32 v[76:77], v[110:111], v[88:89] op_sel_hi:[1,0]
	v_lshl_add_u64 v[48:49], v[48:49], 0, s[8:9]
	s_waitcnt vmcnt(2)
	v_pk_fma_f32 v[18:19], v[22:23], v[74:75], v[18:19]
	v_pk_fma_f32 v[16:17], v[20:21], v[70:71], v[16:17]
	s_waitcnt vmcnt(0)
	v_pk_fma_f32 v[22:23], v[26:27], v[76:77], v[30:31]
	v_pk_fma_f32 v[20:21], v[24:25], v[72:73], v[28:29]
	v_cndmask_b32_e64 v17, v68, v17, s[0:1]
	v_cndmask_b32_e64 v16, v68, v16, s[0:1]
	v_cndmask_b32_e64 v19, v68, v19, s[0:1]
	v_cndmask_b32_e64 v18, v68, v18, s[0:1]
	v_cndmask_b32_e64 v21, v68, v21, s[0:1]
	v_cndmask_b32_e64 v20, v68, v20, s[0:1]
	v_cndmask_b32_e64 v23, v68, v23, s[0:1]
	v_cndmask_b32_e64 v22, v68, v22, s[0:1]
	global_store_dwordx4 v[86:87], v[16:19], off nt
	global_store_dwordx4 v[86:87], v[20:23], off offset:16 nt
	global_load_dwordx4 v[70:73], v[46:47], off
	global_load_dwordx4 v[74:77], v[44:45], off
	global_load_dwordx4 v[78:81], v[44:45], off offset:16
	global_load_dwordx4 v[82:85], v[46:47], off offset:16
	v_mov_b32_e32 v28, v4
	v_mov_b32_e32 v29, v5
	v_mov_b32_e32 v16, v0
	v_mov_b32_e32 v17, v1
	v_pk_mul_f32 v[0:1], v[52:53], v[88:89] op_sel_hi:[1,0]
	v_pk_mul_f32 v[4:5], v[54:55], v[88:89] op_sel_hi:[1,0]
	v_mov_b32_e32 v30, v6
	v_mov_b32_e32 v31, v7
	v_mov_b32_e32 v24, v8
	v_mov_b32_e32 v25, v9
	v_mov_b32_e32 v26, v10
	v_mov_b32_e32 v27, v11
	v_pk_mul_f32 v[6:7], v[56:57], v[88:89] op_sel_hi:[1,0]
	v_pk_mul_f32 v[8:9], v[58:59], v[88:89] op_sel:[1,0] op_sel_hi:[0,0]
	v_mov_b32_e32 v20, v12
	v_mov_b32_e32 v21, v13
	v_mov_b32_e32 v22, v14
	v_mov_b32_e32 v23, v15
	v_mov_b32_e32 v18, v2
	v_mov_b32_e32 v19, v3
	s_waitcnt vmcnt(2)
	v_pk_fma_f32 v[10:11], v[76:77], v[4:5], v[72:73]
	v_pk_fma_f32 v[0:1], v[74:75], v[0:1], v[70:71]
	s_waitcnt vmcnt(0)
	v_pk_fma_f32 v[12:13], v[80:81], v[8:9], v[84:85]
	v_pk_fma_f32 v[8:9], v[78:79], v[6:7], v[82:83]
	v_cndmask_b32_e64 v5, v68, v1, s[0:1]
	v_cndmask_b32_e64 v4, v68, v0, s[0:1]
	v_cndmask_b32_e64 v7, v68, v11, s[0:1]
	v_cndmask_b32_e64 v6, v68, v10, s[0:1]
	v_cndmask_b32_e64 v9, v68, v9, s[0:1]
	v_cndmask_b32_e64 v8, v68, v8, s[0:1]
	v_cndmask_b32_e64 v11, v68, v13, s[0:1]
	v_cndmask_b32_e64 v10, v68, v12, s[0:1]
	global_store_dwordx4 v[86:87], v[4:7], off offset:2048 nt
	global_store_dwordx4 v[86:87], v[8:11], off offset:2064 nt
	s_cbranch_vccz .LBB0_1076
